# baseline (speedup 1.0000x reference)
; #define LDA(dst, b, h) for (int m = 0; m < 4; ++m) for (int k = 0; k < 2; ++k) \
;     dst[m][k] = *reinterpret_cast<const bf16x8*>((char*)SA(b, h) + lds_byte(wr * 64 + m * 16 + fr, k * 32 + fq * 8))
; #define LDB(dst, b, h) for (int n = 0; n < 2; ++n) for (int k = 0; k < 2; ++k) \
;     dst[n][k] = *reinterpret_cast<const bf16x8*>((char*)SB(b, h) + lds_byte(wc * 32 + n * 16 + fr, k * 32 + fq * 8))
; #define MMA(ai, bj, At, Bt_) do { __builtin_amdgcn_s_setprio(1); \
;     for (int m = 0; m < 4; ++m) for (int n = 0; n < 2; ++n) for (int k = 0; k < 2; ++k) \
;       acc[ai][bj][m][n] = __builtin_amdgcn_mfma_f32_16x16x32_bf16(At[m][k], Bt_[n][k], acc[ai][bj][m][n], 0, 0, 0); \
;     __builtin_amdgcn_s_setprio(0); } while (0)
; #define WAIT_L(n) asm volatile("s_waitcnt lgkmcnt(" #n ")" ::: "memory")
; #define BAR __builtin_amdgcn_s_barrier()
; #define SCHED __builtin_amdgcn_sched_barrier(0)
;     ...
;       LDB(B0, 0, 0); SCHED; LDA(At, 0, 0); STAGE(SA(1, 1), A, brow + HALF, t + 1);
;       WAIT_L(8); BAR; WAIT_L(0); MMA(0, 0, At, B0); BAR; SCHED;
;       LDB(B1, 0, 1); STAGE(SB(0, 0), Bt, bcol, t + 2);
;       BAR; WAIT_L(0); MMA(0, 1, At, B1); BAR;
;       LDA(At, 0, 1); STAGE(SA(0, 0), A, brow, t + 2);
;       BAR; WAIT_L(0); MMA(1, 0, At, B0); BAR; SCHED;
.LBB0_98:
	v_add_u32_e32 v143, s2, v142
	ds_read_b128 v[146:149], v143
	ds_read_b128 v[150:153], v143 offset:1024
	ds_read_b128 v[154:157], v143 offset:2048
	ds_read_b128 v[158:161], v143 offset:3072
	s_add_u32 s66, s55, s4
	s_addc_u32 s67, s57, s5
	s_add_i32 s63, s15, 0xc000
	ds_read_b128 v[162:165], v133
	ds_read_b128 v[184:187], v133 offset:1024
	ds_read_b128 v[188:191], v134
	ds_read_b128 v[192:195], v134 offset:1024
	ds_read_b128 v[196:199], v137
	ds_read_b128 v[200:203], v137 offset:1024
	ds_read_b128 v[204:207], v139
	ds_read_b128 v[208:211], v139 offset:1024
	s_mov_b32 m0, s63
	v_lshl_add_u64 v[144:145], s[66:67], 0, v[0:1]
	s_add_i32 s59, s15, 0xe000
	global_load_lds_dwordx4 v[144:145], off
	v_lshl_add_u64 v[144:145], s[66:67], 0, v[140:141]
	s_mov_b32 m0, s59
	s_nop 0
	global_load_lds_dwordx4 v[144:145], off
	s_barrier
	s_waitcnt lgkmcnt(0)
	s_waitcnt lgkmcnt(0)
	v_mfma_f32_16x16x32_bf16 v[126:129], v[162:165], v[146:149], v[126:129]
	v_mfma_f32_16x16x32_bf16 v[122:125], v[162:165], v[154:157], v[122:125]
	v_mfma_f32_16x16x32_bf16 v[118:121], v[188:191], v[146:149], v[118:121]
	v_mfma_f32_16x16x32_bf16 v[114:117], v[188:191], v[154:157], v[114:117]
	v_mfma_f32_16x16x32_bf16 v[110:113], v[196:199], v[146:149], v[110:113]
	v_mfma_f32_16x16x32_bf16 v[106:109], v[196:199], v[154:157], v[106:109]
	v_mfma_f32_16x16x32_bf16 v[102:105], v[204:207], v[146:149], v[102:105]
	v_mfma_f32_16x16x32_bf16 v[98:101], v[204:207], v[154:157], v[98:101]
	v_mfma_f32_16x16x32_bf16 v[126:129], v[184:187], v[150:153], v[126:129]
	v_mfma_f32_16x16x32_bf16 v[122:125], v[184:187], v[158:161], v[122:125]
	v_mfma_f32_16x16x32_bf16 v[118:121], v[192:195], v[150:153], v[118:121]
	v_mfma_f32_16x16x32_bf16 v[114:117], v[192:195], v[158:161], v[114:117]
	v_mfma_f32_16x16x32_bf16 v[110:113], v[200:203], v[150:153], v[110:113]
	v_mfma_f32_16x16x32_bf16 v[106:109], v[200:203], v[158:161], v[106:109]
	v_mfma_f32_16x16x32_bf16 v[102:105], v[208:211], v[150:153], v[102:105]
	v_mfma_f32_16x16x32_bf16 v[98:101], v[208:211], v[158:161], v[98:101]
	s_barrier
	s_add_i32 s58, s58, 2
	s_add_u32 s65, s50, s4
	s_addc_u32 s70, s51, s5
	s_add_u32 s66, s65, 0x100
	v_add_u32_e32 v144, s76, v142
	s_addc_u32 s67, s70, 0
	s_mov_b32 m0, s16
	ds_read_b128 v[212:215], v144
	ds_read_b128 v[216:219], v144 offset:1024
	ds_read_b128 v[220:223], v144 offset:2048
	ds_read_b128 v[224:227], v144 offset:3072
	s_nop 0
	v_lshl_add_u64 v[166:167], s[66:67], 0, v[0:1]
	global_load_lds_dwordx4 v[166:167], off
	v_lshl_add_u64 v[166:167], s[66:67], 0, v[140:141]
	s_mov_b32 m0, s17
	s_nop 0
	global_load_lds_dwordx4 v[166:167], off
	s_barrier
	s_waitcnt lgkmcnt(0)
	s_waitcnt lgkmcnt(0)
	v_mfma_f32_16x16x32_bf16 v[94:97], v[162:165], v[212:215], v[94:97]
	v_mfma_f32_16x16x32_bf16 v[90:93], v[162:165], v[220:223], v[90:93]
	v_mfma_f32_16x16x32_bf16 v[86:89], v[188:191], v[212:215], v[86:89]
	v_mfma_f32_16x16x32_bf16 v[82:85], v[188:191], v[220:223], v[82:85]
	v_mfma_f32_16x16x32_bf16 v[78:81], v[196:199], v[212:215], v[78:81]
	v_mfma_f32_16x16x32_bf16 v[74:77], v[196:199], v[220:223], v[74:77]
	v_mfma_f32_16x16x32_bf16 v[70:73], v[204:207], v[212:215], v[70:73]
	v_mfma_f32_16x16x32_bf16 v[66:69], v[204:207], v[220:223], v[66:69]
	v_mfma_f32_16x16x32_bf16 v[94:97], v[184:187], v[216:219], v[94:97]
	v_mfma_f32_16x16x32_bf16 v[90:93], v[184:187], v[224:227], v[90:93]
	v_mfma_f32_16x16x32_bf16 v[86:89], v[192:195], v[216:219], v[86:89]
	v_mfma_f32_16x16x32_bf16 v[82:85], v[192:195], v[224:227], v[82:85]
	v_mfma_f32_16x16x32_bf16 v[78:81], v[200:203], v[216:219], v[78:81]
	v_mfma_f32_16x16x32_bf16 v[74:77], v[200:203], v[224:227], v[74:77]
	v_mfma_f32_16x16x32_bf16 v[70:73], v[208:211], v[216:219], v[70:73]
	v_mfma_f32_16x16x32_bf16 v[66:69], v[208:211], v[224:227], v[66:69]
	s_add_u32 s71, s44, s4
	s_addc_u32 s72, s45, s5
	s_add_u32 s66, s71, 0x100
	s_addc_u32 s67, s72, 0
	s_mov_b32 m0, s15
	s_barrier
	ds_read_b128 v[162:165], v133 offset:16384
	ds_read_b128 v[184:187], v133 offset:17408
	ds_read_b128 v[188:191], v134 offset:16384
	ds_read_b128 v[192:195], v134 offset:17408
	ds_read_b128 v[196:199], v137 offset:16384
	ds_read_b128 v[200:203], v137 offset:17408
	ds_read_b128 v[204:207], v139 offset:16384
	ds_read_b128 v[208:211], v139 offset:17408
	s_nop 0
	v_lshl_add_u64 v[166:167], s[66:67], 0, v[0:1]
	global_load_lds_dwordx4 v[166:167], off
	v_lshl_add_u64 v[166:167], s[66:67], 0, v[140:141]
	s_mov_b32 m0, s18
	s_nop 0
	global_load_lds_dwordx4 v[166:167], off
	s_barrier
	s_waitcnt lgkmcnt(0)
	s_waitcnt lgkmcnt(0)
	v_mfma_f32_16x16x32_bf16 v[62:65], v[162:165], v[146:149], v[62:65]
	v_mfma_f32_16x16x32_bf16 v[58:61], v[162:165], v[154:157], v[58:61]
	v_mfma_f32_16x16x32_bf16 v[54:57], v[188:191], v[146:149], v[54:57]
	v_mfma_f32_16x16x32_bf16 v[50:53], v[188:191], v[154:157], v[50:53]
	v_mfma_f32_16x16x32_bf16 v[46:49], v[196:199], v[146:149], v[46:49]
	v_mfma_f32_16x16x32_bf16 v[42:45], v[196:199], v[154:157], v[42:45]
	v_mfma_f32_16x16x32_bf16 v[38:41], v[204:207], v[146:149], v[38:41]
	v_mfma_f32_16x16x32_bf16 v[34:37], v[204:207], v[154:157], v[34:37]
	v_mfma_f32_16x16x32_bf16 v[62:65], v[184:187], v[150:153], v[62:65]
	v_mfma_f32_16x16x32_bf16 v[58:61], v[184:187], v[158:161], v[58:61]
	v_mfma_f32_16x16x32_bf16 v[54:57], v[192:195], v[150:153], v[54:57]
	v_mfma_f32_16x16x32_bf16 v[50:53], v[192:195], v[158:161], v[50:53]
	v_mfma_f32_16x16x32_bf16 v[46:49], v[200:203], v[150:153], v[46:49]
	v_mfma_f32_16x16x32_bf16 v[42:45], v[200:203], v[158:161], v[42:45]
	v_mfma_f32_16x16x32_bf16 v[38:41], v[208:211], v[150:153], v[38:41]
	v_mfma_f32_16x16x32_bf16 v[34:37], v[208:211], v[158:161], v[34:37]
	s_barrier
; #define LDA(dst, b, h) for (int m = 0; m < 4; ++m) for (int k = 0; k < 2; ++k) \
;     dst[m][k] = *reinterpret_cast<const bf16x8*>((char*)SA(b, h) + lds_byte(wr * 64 + m * 16 + fr, k * 32 + fq * 8))
; #define LDB(dst, b, h) for (int n = 0; n < 2; ++n) for (int k = 0; k < 2; ++k) \
;     dst[n][k] = *reinterpret_cast<const bf16x8*>((char*)SB(b, h) + lds_byte(wc * 32 + n * 16 + fr, k * 32 + fq * 8))
; #define MMA(ai, bj, At, Bt_) do { __builtin_amdgcn_s_setprio(1); \
;     for (int m = 0; m < 4; ++m) for (int n = 0; n < 2; ++n) for (int k = 0; k < 2; ++k) \
;       acc[ai][bj][m][n] = __builtin_amdgcn_mfma_f32_16x16x32_bf16(At[m][k], Bt_[n][k], acc[ai][bj][m][n], 0, 0, 0); \
;     __builtin_amdgcn_s_setprio(0); } while (0)
; #define WAIT_V(n) asm volatile("s_waitcnt vmcnt(" #n ")" ::: "memory")
; #define WAIT_L(n) asm volatile("s_waitcnt lgkmcnt(" #n ")" ::: "memory")
; #define BAR __builtin_amdgcn_s_barrier()
; #define SCHED __builtin_amdgcn_sched_barrier(0)
;     ...
;       STAGE(SB(0, 1), Bt, bcol + HALF, t + 2);
;       WAIT_V(6); BAR; MMA(1, 1, At, B1); BAR;
;       LDB(B0, 1, 0); SCHED; LDA(At, 1, 0); STAGE(SA(0, 1), A, brow + HALF, t + 2);
;       WAIT_L(8); BAR; WAIT_L(0); MMA(0, 0, At, B0); BAR; SCHED;
;       LDB(B1, 1, 1); STAGE(SB(1, 0), Bt, bcol, t + 3);
;       BAR; WAIT_L(0); MMA(0, 1, At, B1); BAR;
;       LDA(At, 1, 1); STAGE(SA(1, 0), A, brow, t + 3);
	s_add_u32 s73, s6, s4
	s_addc_u32 s82, s7, s5
	s_add_u32 s66, s73, 0x160100
	s_addc_u32 s67, s82, 0
	s_mov_b32 m0, s19
	s_nop 0
	v_lshl_add_u64 v[146:147], s[66:67], 0, v[0:1]
	global_load_lds_dwordx4 v[146:147], off
	v_lshl_add_u64 v[146:147], s[66:67], 0, v[140:141]
	s_mov_b32 m0, s21
	s_nop 0
	global_load_lds_dwordx4 v[146:147], off
	s_waitcnt vmcnt(6)
	s_barrier
	v_mfma_f32_16x16x32_bf16 v[30:33], v[162:165], v[212:215], v[30:33]
	v_mfma_f32_16x16x32_bf16 v[26:29], v[162:165], v[220:223], v[26:29]
	v_mfma_f32_16x16x32_bf16 v[22:25], v[188:191], v[212:215], v[22:25]
	v_mfma_f32_16x16x32_bf16 v[18:21], v[188:191], v[220:223], v[18:21]
	v_mfma_f32_16x16x32_bf16 v[14:17], v[196:199], v[212:215], v[14:17]
	v_mfma_f32_16x16x32_bf16 v[10:13], v[196:199], v[220:223], v[10:13]
	v_mfma_f32_16x16x32_bf16 v[6:9], v[204:207], v[212:215], v[6:9]
	v_mfma_f32_16x16x32_bf16 v[2:5], v[204:207], v[220:223], v[2:5]
	v_mfma_f32_16x16x32_bf16 v[30:33], v[184:187], v[216:219], v[30:33]
	v_mfma_f32_16x16x32_bf16 v[26:29], v[184:187], v[224:227], v[26:29]
	v_mfma_f32_16x16x32_bf16 v[22:25], v[192:195], v[216:219], v[22:25]
	v_mfma_f32_16x16x32_bf16 v[18:21], v[192:195], v[224:227], v[18:21]
	v_mfma_f32_16x16x32_bf16 v[14:17], v[200:203], v[216:219], v[14:17]
	v_mfma_f32_16x16x32_bf16 v[10:13], v[200:203], v[224:227], v[10:13]
	v_mfma_f32_16x16x32_bf16 v[6:9], v[208:211], v[216:219], v[6:9]
	v_mfma_f32_16x16x32_bf16 v[2:5], v[208:211], v[224:227], v[2:5]
	v_add_u32_e32 v145, s77, v142
	s_barrier
	ds_read_b128 v[148:151], v145
	ds_read_b128 v[152:155], v145 offset:1024
	ds_read_b128 v[156:159], v145 offset:2048
	ds_read_b128 v[160:163], v145 offset:3072
	s_add_u32 s66, s71, 0x160100
	s_addc_u32 s67, s72, 0
	s_mov_b32 m0, s30
	ds_read_b128 v[164:167], v133 offset:32768
	ds_read_b128 v[184:187], v133 offset:33792
	ds_read_b128 v[188:191], v134 offset:32768
	ds_read_b128 v[192:195], v134 offset:33792
	ds_read_b128 v[196:199], v137 offset:32768
	ds_read_b128 v[200:203], v137 offset:33792
	ds_read_b128 v[204:207], v139 offset:32768
	ds_read_b128 v[208:211], v139 offset:33792
	s_nop 0
	v_lshl_add_u64 v[146:147], s[66:67], 0, v[0:1]
	global_load_lds_dwordx4 v[146:147], off
	v_lshl_add_u64 v[146:147], s[66:67], 0, v[140:141]
	s_mov_b32 m0, s31
	s_nop 0
	global_load_lds_dwordx4 v[146:147], off
	s_barrier
	s_waitcnt lgkmcnt(0)
	s_waitcnt lgkmcnt(0)
	v_mfma_f32_16x16x32_bf16 v[126:129], v[164:167], v[148:151], v[126:129]
	v_mfma_f32_16x16x32_bf16 v[122:125], v[164:167], v[156:159], v[122:125]
	v_mfma_f32_16x16x32_bf16 v[118:121], v[188:191], v[148:151], v[118:121]
	v_mfma_f32_16x16x32_bf16 v[114:117], v[188:191], v[156:159], v[114:117]
	v_mfma_f32_16x16x32_bf16 v[110:113], v[196:199], v[148:151], v[110:113]
	v_mfma_f32_16x16x32_bf16 v[106:109], v[196:199], v[156:159], v[106:109]
	v_mfma_f32_16x16x32_bf16 v[102:105], v[204:207], v[148:151], v[102:105]
	v_mfma_f32_16x16x32_bf16 v[98:101], v[204:207], v[156:159], v[98:101]
	v_mfma_f32_16x16x32_bf16 v[126:129], v[184:187], v[152:155], v[126:129]
	v_mfma_f32_16x16x32_bf16 v[122:125], v[184:187], v[160:163], v[122:125]
	v_mfma_f32_16x16x32_bf16 v[118:121], v[192:195], v[152:155], v[118:121]
	v_mfma_f32_16x16x32_bf16 v[114:117], v[192:195], v[160:163], v[114:117]
	v_mfma_f32_16x16x32_bf16 v[110:113], v[200:203], v[152:155], v[110:113]
	v_mfma_f32_16x16x32_bf16 v[106:109], v[200:203], v[160:163], v[106:109]
	v_mfma_f32_16x16x32_bf16 v[102:105], v[208:211], v[152:155], v[102:105]
	v_mfma_f32_16x16x32_bf16 v[98:101], v[208:211], v[160:163], v[98:101]
	s_barrier
	s_add_u32 s66, s65, 0x180
	v_add_u32_e32 v146, s78, v142
	s_addc_u32 s67, s70, 0
	s_mov_b32 m0, s34
	ds_read_b128 v[212:215], v146
	ds_read_b128 v[216:219], v146 offset:1024
	ds_read_b128 v[220:223], v146 offset:2048
	ds_read_b128 v[224:227], v146 offset:3072
	s_nop 0
	v_lshl_add_u64 v[228:229], s[66:67], 0, v[0:1]
	global_load_lds_dwordx4 v[228:229], off
	v_lshl_add_u64 v[228:229], s[66:67], 0, v[140:141]
	s_mov_b32 m0, s35
	s_nop 0
	global_load_lds_dwordx4 v[228:229], off
	s_barrier
	s_waitcnt lgkmcnt(0)
	s_waitcnt lgkmcnt(0)
	v_mfma_f32_16x16x32_bf16 v[94:97], v[164:167], v[212:215], v[94:97]
	v_mfma_f32_16x16x32_bf16 v[90:93], v[164:167], v[220:223], v[90:93]
	v_mfma_f32_16x16x32_bf16 v[86:89], v[188:191], v[212:215], v[86:89]
	v_mfma_f32_16x16x32_bf16 v[82:85], v[188:191], v[220:223], v[82:85]
	v_mfma_f32_16x16x32_bf16 v[78:81], v[196:199], v[212:215], v[78:81]
	v_mfma_f32_16x16x32_bf16 v[74:77], v[196:199], v[220:223], v[74:77]
	v_mfma_f32_16x16x32_bf16 v[70:73], v[204:207], v[212:215], v[70:73]
	v_mfma_f32_16x16x32_bf16 v[66:69], v[204:207], v[220:223], v[66:69]
	v_mfma_f32_16x16x32_bf16 v[94:97], v[184:187], v[216:219], v[94:97]
	v_mfma_f32_16x16x32_bf16 v[90:93], v[184:187], v[224:227], v[90:93]
	v_mfma_f32_16x16x32_bf16 v[86:89], v[192:195], v[216:219], v[86:89]
	v_mfma_f32_16x16x32_bf16 v[82:85], v[192:195], v[224:227], v[82:85]
	v_mfma_f32_16x16x32_bf16 v[78:81], v[200:203], v[216:219], v[78:81]
	v_mfma_f32_16x16x32_bf16 v[74:77], v[200:203], v[224:227], v[74:77]
	v_mfma_f32_16x16x32_bf16 v[70:73], v[208:211], v[216:219], v[70:73]
	v_mfma_f32_16x16x32_bf16 v[66:69], v[208:211], v[224:227], v[66:69]
	s_add_u32 s66, s71, 0x180
	s_addc_u32 s67, s72, 0
	s_mov_b32 m0, s37
	s_barrier
	ds_read_b128 v[164:167], v133 offset:49152
	ds_read_b128 v[184:187], v133 offset:50176
	ds_read_b128 v[188:191], v134 offset:49152
	ds_read_b128 v[192:195], v134 offset:50176
	ds_read_b128 v[196:199], v137 offset:49152
	ds_read_b128 v[200:203], v137 offset:50176
	ds_read_b128 v[204:207], v139 offset:49152
	ds_read_b128 v[208:211], v139 offset:50176
	s_nop 0
	v_lshl_add_u64 v[228:229], s[66:67], 0, v[0:1]
	global_load_lds_dwordx4 v[228:229], off
	v_lshl_add_u64 v[228:229], s[66:67], 0, v[140:141]
	s_mov_b32 m0, s38
	s_nop 0
	global_load_lds_dwordx4 v[228:229], off
	s_barrier
; #define LDA(dst, b, h) for (int m = 0; m < 4; ++m) for (int k = 0; k < 2; ++k) \
;     dst[m][k] = *reinterpret_cast<const bf16x8*>((char*)SA(b, h) + lds_byte(wr * 64 + m * 16 + fr, k * 32 + fq * 8))
; #define LDB(dst, b, h) for (int n = 0; n < 2; ++n) for (int k = 0; k < 2; ++k) \
;     dst[n][k] = *reinterpret_cast<const bf16x8*>((char*)SB(b, h) + lds_byte(wc * 32 + n * 16 + fr, k * 32 + fq * 8))
; #define MMA(ai, bj, At, Bt_) do { __builtin_amdgcn_s_setprio(1); \
;     for (int m = 0; m < 4; ++m) for (int n = 0; n < 2; ++n) for (int k = 0; k < 2; ++k) \
;       acc[ai][bj][m][n] = __builtin_amdgcn_mfma_f32_16x16x32_bf16(At[m][k], Bt_[n][k], acc[ai][bj][m][n], 0, 0, 0); \
;     __builtin_amdgcn_s_setprio(0); } while (0)
; #define WAIT_V(n) asm volatile("s_waitcnt vmcnt(" #n ")" ::: "memory")
; #define WAIT_L(n) asm volatile("s_waitcnt lgkmcnt(" #n ")" ::: "memory")
; #define BAR __builtin_amdgcn_s_barrier()
; #define SCHED __builtin_amdgcn_sched_barrier(0)
;     ...
;       BAR; WAIT_L(0); MMA(1, 0, At, B0); BAR; SCHED;
;       STAGE(SB(1, 1), Bt, bcol + HALF, t + 3);
;       WAIT_V(6); BAR; MMA(1, 1, At, B1); BAR;
;     }
;     { LDB(B0, 0, 0); LDA(At, 0, 0); STAGE(SA(1, 1), A, brow + HALF, nt - 1);
;       BAR; WAIT_L(0); MMA(0, 0, At, B0); BAR;
;       LDB(B1, 0, 1); BAR; WAIT_L(0); MMA(0, 1, At, B1); BAR;
	s_waitcnt lgkmcnt(0)
	s_waitcnt lgkmcnt(0)
	v_mfma_f32_16x16x32_bf16 v[62:65], v[164:167], v[148:151], v[62:65]
	v_mfma_f32_16x16x32_bf16 v[58:61], v[164:167], v[156:159], v[58:61]
	v_mfma_f32_16x16x32_bf16 v[54:57], v[188:191], v[148:151], v[54:57]
	v_mfma_f32_16x16x32_bf16 v[50:53], v[188:191], v[156:159], v[50:53]
	v_mfma_f32_16x16x32_bf16 v[46:49], v[196:199], v[148:151], v[46:49]
	v_mfma_f32_16x16x32_bf16 v[42:45], v[196:199], v[156:159], v[42:45]
	v_mfma_f32_16x16x32_bf16 v[38:41], v[204:207], v[148:151], v[38:41]
	v_mfma_f32_16x16x32_bf16 v[34:37], v[204:207], v[156:159], v[34:37]
	v_mfma_f32_16x16x32_bf16 v[62:65], v[184:187], v[152:155], v[62:65]
	v_mfma_f32_16x16x32_bf16 v[58:61], v[184:187], v[160:163], v[58:61]
	v_mfma_f32_16x16x32_bf16 v[54:57], v[192:195], v[152:155], v[54:57]
	v_mfma_f32_16x16x32_bf16 v[50:53], v[192:195], v[160:163], v[50:53]
	v_mfma_f32_16x16x32_bf16 v[46:49], v[200:203], v[152:155], v[46:49]
	v_mfma_f32_16x16x32_bf16 v[42:45], v[200:203], v[160:163], v[42:45]
	v_mfma_f32_16x16x32_bf16 v[38:41], v[208:211], v[152:155], v[38:41]
	v_mfma_f32_16x16x32_bf16 v[34:37], v[208:211], v[160:163], v[34:37]
	s_barrier
	s_add_u32 s66, s73, 0x160180
	s_addc_u32 s67, s82, 0
	s_mov_b32 m0, s41
	s_nop 0
	v_lshl_add_u64 v[148:149], s[66:67], 0, v[0:1]
	global_load_lds_dwordx4 v[148:149], off
	v_lshl_add_u64 v[148:149], s[66:67], 0, v[140:141]
	s_mov_b32 m0, s42
	s_nop 0
	global_load_lds_dwordx4 v[148:149], off
	s_waitcnt vmcnt(6)
	s_barrier
	v_mfma_f32_16x16x32_bf16 v[30:33], v[164:167], v[212:215], v[30:33]
	v_mfma_f32_16x16x32_bf16 v[26:29], v[164:167], v[220:223], v[26:29]
	v_mfma_f32_16x16x32_bf16 v[22:25], v[188:191], v[212:215], v[22:25]
	v_mfma_f32_16x16x32_bf16 v[18:21], v[188:191], v[220:223], v[18:21]
	v_mfma_f32_16x16x32_bf16 v[14:17], v[196:199], v[212:215], v[14:17]
	v_mfma_f32_16x16x32_bf16 v[10:13], v[196:199], v[220:223], v[10:13]
	v_mfma_f32_16x16x32_bf16 v[6:9], v[204:207], v[212:215], v[6:9]
	v_mfma_f32_16x16x32_bf16 v[2:5], v[204:207], v[220:223], v[2:5]
	v_mfma_f32_16x16x32_bf16 v[30:33], v[184:187], v[216:219], v[30:33]
	v_mfma_f32_16x16x32_bf16 v[26:29], v[184:187], v[224:227], v[26:29]
	v_mfma_f32_16x16x32_bf16 v[22:25], v[192:195], v[216:219], v[22:25]
	v_mfma_f32_16x16x32_bf16 v[18:21], v[192:195], v[224:227], v[18:21]
	v_mfma_f32_16x16x32_bf16 v[14:17], v[200:203], v[216:219], v[14:17]
	v_mfma_f32_16x16x32_bf16 v[10:13], v[200:203], v[224:227], v[10:13]
	v_mfma_f32_16x16x32_bf16 v[6:9], v[208:211], v[216:219], v[6:9]
	v_mfma_f32_16x16x32_bf16 v[2:5], v[208:211], v[224:227], v[2:5]
	s_add_u32 s6, s6, 0x100
	s_addc_u32 s7, s7, 0
	s_add_u32 s44, s44, 0x100
	s_addc_u32 s45, s45, 0
	s_add_u32 s50, s50, 0x100
	s_addc_u32 s51, s51, 0
	s_add_u32 s55, s55, 0x100
	s_addc_u32 s57, s57, 0
	s_cmp_ge_u32 s58, s43
	s_barrier
	s_cbranch_scc0 .LBB0_98
	s_add_i32 s4, s48, s14
	s_add_i32 s48, s4, -1
	s_lshl_b64 s[4:5], s[48:49], 7
	s_add_u32 s4, s22, s4
	s_addc_u32 s5, s23, s5
	s_add_u32 s4, s4, s40
	s_addc_u32 s5, s5, s39
	s_mov_b32 m0, s63
	ds_read_b128 v[148:151], v143
	ds_read_b128 v[152:155], v143 offset:1024
	ds_read_b128 v[156:159], v143 offset:2048
	ds_read_b128 v[160:163], v143 offset:3072
	ds_read_b128 v[164:167], v133
	ds_read_b128 v[184:187], v133 offset:1024
	ds_read_b128 v[188:191], v134
	ds_read_b128 v[192:195], v134 offset:1024
	ds_read_b128 v[196:199], v137
	ds_read_b128 v[200:203], v137 offset:1024
	ds_read_b128 v[204:207], v139
	ds_read_b128 v[208:211], v139 offset:1024
	s_nop 0
	v_lshl_add_u64 v[142:143], s[4:5], 0, v[0:1]
	global_load_lds_dwordx4 v[142:143], off
	v_lshl_add_u64 v[140:141], s[4:5], 0, v[140:141]
	s_mov_b32 m0, s59
	s_nop 0
	global_load_lds_dwordx4 v[140:141], off
	s_barrier
	s_waitcnt lgkmcnt(0)
	s_setprio 1
	s_waitcnt lgkmcnt(0)
	v_mfma_f32_16x16x32_bf16 v[126:129], v[164:167], v[148:151], v[126:129]
	v_mfma_f32_16x16x32_bf16 v[122:125], v[164:167], v[156:159], v[122:125]
	v_mfma_f32_16x16x32_bf16 v[118:121], v[188:191], v[148:151], v[118:121]
	v_mfma_f32_16x16x32_bf16 v[110:113], v[196:199], v[148:151], v[110:113]
	v_mfma_f32_16x16x32_bf16 v[106:109], v[196:199], v[156:159], v[106:109]
	v_mfma_f32_16x16x32_bf16 v[102:105], v[204:207], v[148:151], v[102:105]
	v_mfma_f32_16x16x32_bf16 v[98:101], v[204:207], v[156:159], v[98:101]
	v_mfma_f32_16x16x32_bf16 v[126:129], v[184:187], v[152:155], v[126:129]
	v_mfma_f32_16x16x32_bf16 v[122:125], v[184:187], v[160:163], v[122:125]
	v_mfma_f32_16x16x32_bf16 v[118:121], v[192:195], v[152:155], v[118:121]
	v_mfma_f32_16x16x32_bf16 v[114:117], v[188:191], v[156:159], v[114:117]
	v_mfma_f32_16x16x32_bf16 v[110:113], v[200:203], v[152:155], v[110:113]
	v_mfma_f32_16x16x32_bf16 v[106:109], v[200:203], v[160:163], v[106:109]
	v_mfma_f32_16x16x32_bf16 v[102:105], v[208:211], v[152:155], v[102:105]
	v_mfma_f32_16x16x32_bf16 v[98:101], v[208:211], v[160:163], v[98:101]
	v_mfma_f32_16x16x32_bf16 v[140:143], v[192:195], v[160:163], v[114:117]
	s_setprio 0
	s_barrier
	s_nop 0
	ds_read_b128 v[114:117], v144
	ds_read_b128 v[212:215], v144 offset:1024
	ds_read_b128 v[216:219], v144 offset:2048
	ds_read_b128 v[220:223], v144 offset:3072
	s_barrier
; #define LDA(dst, b, h) for (int m = 0; m < 4; ++m) for (int k = 0; k < 2; ++k) \
;     dst[m][k] = *reinterpret_cast<const bf16x8*>((char*)SA(b, h) + lds_byte(wr * 64 + m * 16 + fr, k * 32 + fq * 8))
; #define LDB(dst, b, h) for (int n = 0; n < 2; ++n) for (int k = 0; k < 2; ++k) \
;     dst[n][k] = *reinterpret_cast<const bf16x8*>((char*)SB(b, h) + lds_byte(wc * 32 + n * 16 + fr, k * 32 + fq * 8))
; #define MMA(ai, bj, At, Bt_) do { __builtin_amdgcn_s_setprio(1); \
;     for (int m = 0; m < 4; ++m) for (int n = 0; n < 2; ++n) for (int k = 0; k < 2; ++k) \
;       acc[ai][bj][m][n] = __builtin_amdgcn_mfma_f32_16x16x32_bf16(At[m][k], Bt_[n][k], acc[ai][bj][m][n], 0, 0, 0); \
;     __builtin_amdgcn_s_setprio(0); } while (0)
; #define WAIT_V(n) asm volatile("s_waitcnt vmcnt(" #n ")" ::: "memory")
; #define WAIT_L(n) asm volatile("s_waitcnt lgkmcnt(" #n ")" ::: "memory")
; #define BAR __builtin_amdgcn_s_barrier()
;     ...
;       LDB(B1, 0, 1); BAR; WAIT_L(0); MMA(0, 1, At, B1); BAR;
;       LDA(At, 0, 1); WAIT_V(4); BAR; WAIT_L(0); MMA(1, 0, At, B0); MMA(1, 1, At, B1); BAR; }
;     { LDB(B0, 1, 0); LDA(At, 1, 0); WAIT_V(2); BAR; WAIT_L(0); MMA(0, 0, At, B0); BAR;
	s_waitcnt lgkmcnt(0)
	s_setprio 1
	s_waitcnt lgkmcnt(0)
	v_mfma_f32_16x16x32_bf16 v[90:93], v[164:167], v[216:219], v[90:93]
	v_mfma_f32_16x16x32_bf16 v[86:89], v[188:191], v[114:117], v[86:89]
	v_mfma_f32_16x16x32_bf16 v[94:97], v[164:167], v[114:117], v[94:97]
	v_mfma_f32_16x16x32_bf16 v[90:93], v[184:187], v[220:223], v[90:93]
	v_mfma_f32_16x16x32_bf16 v[86:89], v[192:195], v[212:215], v[86:89]
	v_mfma_f32_16x16x32_bf16 v[82:85], v[188:191], v[216:219], v[82:85]
	v_mfma_f32_16x16x32_bf16 v[78:81], v[196:199], v[114:117], v[78:81]
	v_mfma_f32_16x16x32_bf16 v[74:77], v[196:199], v[216:219], v[74:77]
	v_mfma_f32_16x16x32_bf16 v[70:73], v[204:207], v[114:117], v[70:73]
	v_mfma_f32_16x16x32_bf16 v[66:69], v[204:207], v[216:219], v[66:69]
	v_mfma_f32_16x16x32_bf16 v[224:227], v[184:187], v[212:215], v[94:97]
	v_mfma_f32_16x16x32_bf16 v[164:167], v[192:195], v[220:223], v[82:85]
	v_mfma_f32_16x16x32_bf16 v[184:187], v[200:203], v[212:215], v[78:81]
	v_mfma_f32_16x16x32_bf16 v[188:191], v[200:203], v[220:223], v[74:77]
	v_mfma_f32_16x16x32_bf16 v[192:195], v[208:211], v[212:215], v[70:73]
	v_mfma_f32_16x16x32_bf16 v[196:199], v[208:211], v[220:223], v[66:69]
	s_setprio 0
	s_barrier
	s_nop 0
	ds_read_b128 v[66:69], v133 offset:16384
	ds_read_b128 v[70:73], v133 offset:17408
	ds_read_b128 v[74:77], v134 offset:16384
	ds_read_b128 v[78:81], v134 offset:17408
	ds_read_b128 v[82:85], v137 offset:16384
	ds_read_b128 v[94:97], v137 offset:17408
	ds_read_b128 v[200:203], v139 offset:16384
	ds_read_b128 v[204:207], v139 offset:17408
	s_waitcnt vmcnt(4)
	s_barrier
	s_waitcnt lgkmcnt(0)
	s_setprio 1
	s_waitcnt lgkmcnt(0)
	v_mfma_f32_16x16x32_bf16 v[62:65], v[66:69], v[148:151], v[62:65]
	v_mfma_f32_16x16x32_bf16 v[58:61], v[66:69], v[156:159], v[58:61]
	v_mfma_f32_16x16x32_bf16 v[54:57], v[74:77], v[148:151], v[54:57]
	v_mfma_f32_16x16x32_bf16 v[50:53], v[74:77], v[156:159], v[50:53]
	v_mfma_f32_16x16x32_bf16 v[46:49], v[82:85], v[148:151], v[46:49]
	v_mfma_f32_16x16x32_bf16 v[42:45], v[82:85], v[156:159], v[42:45]
	v_mfma_f32_16x16x32_bf16 v[38:41], v[200:203], v[148:151], v[38:41]
	v_mfma_f32_16x16x32_bf16 v[34:37], v[200:203], v[156:159], v[34:37]
	v_mfma_f32_16x16x32_bf16 v[62:65], v[70:73], v[152:155], v[62:65]
	v_mfma_f32_16x16x32_bf16 v[58:61], v[70:73], v[160:163], v[58:61]
	v_mfma_f32_16x16x32_bf16 v[54:57], v[78:81], v[152:155], v[54:57]
	v_mfma_f32_16x16x32_bf16 v[50:53], v[78:81], v[160:163], v[50:53]
	v_mfma_f32_16x16x32_bf16 v[46:49], v[94:97], v[152:155], v[46:49]
	v_mfma_f32_16x16x32_bf16 v[42:45], v[94:97], v[160:163], v[42:45]
	v_mfma_f32_16x16x32_bf16 v[38:41], v[204:207], v[152:155], v[38:41]
	v_mfma_f32_16x16x32_bf16 v[34:37], v[204:207], v[160:163], v[34:37]
	s_setprio 0
	s_setprio 1
	v_mfma_f32_16x16x32_bf16 v[30:33], v[66:69], v[114:117], v[30:33]
	v_mfma_f32_16x16x32_bf16 v[26:29], v[66:69], v[216:219], v[26:29]
	v_mfma_f32_16x16x32_bf16 v[22:25], v[74:77], v[114:117], v[22:25]
	v_mfma_f32_16x16x32_bf16 v[18:21], v[74:77], v[216:219], v[18:21]
	v_mfma_f32_16x16x32_bf16 v[14:17], v[82:85], v[114:117], v[14:17]
	v_mfma_f32_16x16x32_bf16 v[10:13], v[82:85], v[216:219], v[10:13]
	v_mfma_f32_16x16x32_bf16 v[6:9], v[200:203], v[114:117], v[6:9]
	v_mfma_f32_16x16x32_bf16 v[2:5], v[200:203], v[216:219], v[2:5]
	v_mfma_f32_16x16x32_bf16 v[148:151], v[70:73], v[212:215], v[30:33]
	v_mfma_f32_16x16x32_bf16 v[152:155], v[70:73], v[220:223], v[26:29]
	v_mfma_f32_16x16x32_bf16 v[156:159], v[78:81], v[212:215], v[22:25]
	v_mfma_f32_16x16x32_bf16 v[160:163], v[78:81], v[220:223], v[18:21]
	v_mfma_f32_16x16x32_bf16 v[208:211], v[94:97], v[212:215], v[14:17]
	v_mfma_f32_16x16x32_bf16 v[228:231], v[94:97], v[220:223], v[10:13]
	v_mfma_f32_16x16x32_bf16 v[212:215], v[204:207], v[212:215], v[6:9]
	v_mfma_f32_16x16x32_bf16 v[200:203], v[204:207], v[220:223], v[2:5]
	s_setprio 0
	s_barrier
	ds_read_b128 v[14:17], v145
	ds_read_b128 v[30:33], v145 offset:1024
	ds_read_b128 v[204:207], v145 offset:2048
	ds_read_b128 v[216:219], v145 offset:3072
	ds_read_b128 v[2:5], v133 offset:32768
	ds_read_b128 v[6:9], v133 offset:33792
	ds_read_b128 v[10:13], v134 offset:32768
	ds_read_b128 v[18:21], v134 offset:33792
	ds_read_b128 v[22:25], v137 offset:32768
	ds_read_b128 v[26:29], v137 offset:33792
	ds_read_b128 v[220:223], v139 offset:32768
	ds_read_b128 v[232:235], v139 offset:33792
	s_waitcnt vmcnt(2)
	s_barrier
; #define LDA(dst, b, h) for (int m = 0; m < 4; ++m) for (int k = 0; k < 2; ++k) \
;     dst[m][k] = *reinterpret_cast<const bf16x8*>((char*)SA(b, h) + lds_byte(wr * 64 + m * 16 + fr, k * 32 + fq * 8))
; #define LDB(dst, b, h) for (int n = 0; n < 2; ++n) for (int k = 0; k < 2; ++k) \
;     dst[n][k] = *reinterpret_cast<const bf16x8*>((char*)SB(b, h) + lds_byte(wc * 32 + n * 16 + fr, k * 32 + fq * 8))
; #define MMA(ai, bj, At, Bt_) do { __builtin_amdgcn_s_setprio(1); \
;     for (int m = 0; m < 4; ++m) for (int n = 0; n < 2; ++n) for (int k = 0; k < 2; ++k) \
;       acc[ai][bj][m][n] = __builtin_amdgcn_mfma_f32_16x16x32_bf16(At[m][k], Bt_[n][k], acc[ai][bj][m][n], 0, 0, 0); \
;     __builtin_amdgcn_s_setprio(0); } while (0)
; #define WAIT_V(n) asm volatile("s_waitcnt vmcnt(" #n ")" ::: "memory")
; #define WAIT_L(n) asm volatile("s_waitcnt lgkmcnt(" #n ")" ::: "memory")
; #define BAR __builtin_amdgcn_s_barrier()
;     ...
;     { LDB(B0, 1, 0); LDA(At, 1, 0); WAIT_V(2); BAR; WAIT_L(0); MMA(0, 0, At, B0); BAR;
;       LDB(B1, 1, 1); WAIT_V(0); BAR; WAIT_L(0); MMA(0, 1, At, B1); BAR;
;       LDA(At, 1, 1); BAR; WAIT_L(0); MMA(1, 0, At, B0); MMA(1, 1, At, B1); BAR; }
;     if (wr == 0) BAR;
	s_waitcnt lgkmcnt(0)
	s_setprio 1
	s_waitcnt lgkmcnt(0)
	v_mfma_f32_16x16x32_bf16 v[66:69], v[2:5], v[14:17], v[126:129]
	v_mfma_f32_16x16x32_bf16 v[114:117], v[6:9], v[30:33], v[66:69]
	v_mfma_f32_16x16x32_bf16 v[66:69], v[2:5], v[204:207], v[122:125]
	v_mfma_f32_16x16x32_bf16 v[126:129], v[6:9], v[216:219], v[66:69]
	v_mfma_f32_16x16x32_bf16 v[66:69], v[10:13], v[14:17], v[118:121]
	v_mfma_f32_16x16x32_bf16 v[82:85], v[18:21], v[30:33], v[66:69]
	v_mfma_f32_16x16x32_bf16 v[66:69], v[10:13], v[204:207], v[140:143]
	v_mfma_f32_16x16x32_bf16 v[94:97], v[18:21], v[216:219], v[66:69]
	v_mfma_f32_16x16x32_bf16 v[66:69], v[22:25], v[14:17], v[110:113]
	v_mfma_f32_16x16x32_bf16 v[74:77], v[26:29], v[30:33], v[66:69]
	v_mfma_f32_16x16x32_bf16 v[66:69], v[22:25], v[204:207], v[106:109]
	v_mfma_f32_16x16x32_bf16 v[78:81], v[26:29], v[216:219], v[66:69]
	v_mfma_f32_16x16x32_bf16 v[66:69], v[220:223], v[14:17], v[102:105]
	v_mfma_f32_16x16x32_bf16 v[70:73], v[220:223], v[204:207], v[98:101]
	v_mfma_f32_16x16x32_bf16 v[66:69], v[232:235], v[30:33], v[66:69]
	v_mfma_f32_16x16x32_bf16 v[70:73], v[232:235], v[216:219], v[70:73]
	s_setprio 0
	s_barrier
	ds_read_b128 v[140:143], v146
	ds_read_b128 v[236:239], v146 offset:1024
	ds_read_b128 v[240:243], v146 offset:2048
	ds_read_b128 v[144:147], v146 offset:3072
	s_waitcnt vmcnt(0)
	s_barrier
	s_waitcnt lgkmcnt(0)
	s_setprio 1
	s_waitcnt lgkmcnt(0)
	v_mfma_f32_16x16x32_bf16 v[98:101], v[2:5], v[140:143], v[224:227]
	v_mfma_f32_16x16x32_bf16 v[2:5], v[2:5], v[240:243], v[90:93]
	v_mfma_f32_16x16x32_bf16 v[118:121], v[6:9], v[144:147], v[2:5]
	v_mfma_f32_16x16x32_bf16 v[2:5], v[10:13], v[140:143], v[86:89]
	v_mfma_f32_16x16x32_bf16 v[102:105], v[18:21], v[236:239], v[2:5]
	v_mfma_f32_16x16x32_bf16 v[2:5], v[10:13], v[240:243], v[164:167]
	v_mfma_f32_16x16x32_bf16 v[122:125], v[18:21], v[144:147], v[2:5]
	v_mfma_f32_16x16x32_bf16 v[2:5], v[22:25], v[140:143], v[184:187]
	v_mfma_f32_16x16x32_bf16 v[90:93], v[26:29], v[236:239], v[2:5]
	v_mfma_f32_16x16x32_bf16 v[2:5], v[22:25], v[240:243], v[188:191]
	v_mfma_f32_16x16x32_bf16 v[110:113], v[26:29], v[144:147], v[2:5]
	v_mfma_f32_16x16x32_bf16 v[2:5], v[220:223], v[140:143], v[192:195]
	v_mfma_f32_16x16x32_bf16 v[86:89], v[232:235], v[236:239], v[2:5]
	v_mfma_f32_16x16x32_bf16 v[2:5], v[220:223], v[240:243], v[196:199]
	v_mfma_f32_16x16x32_bf16 v[98:101], v[6:9], v[236:239], v[98:101]
	v_mfma_f32_16x16x32_bf16 v[106:109], v[232:235], v[144:147], v[2:5]
	s_setprio 0
	s_barrier
	ds_read_b128 v[164:167], v133 offset:49152
	ds_read_b128 v[184:187], v133 offset:50176
	ds_read_b128 v[188:191], v134 offset:49152
	ds_read_b128 v[192:195], v134 offset:50176
	ds_read_b128 v[196:199], v137 offset:49152
	ds_read_b128 v[220:223], v137 offset:50176
	ds_read_b128 v[224:227], v139 offset:49152
	ds_read_b128 v[232:235], v139 offset:50176
	s_barrier
	s_waitcnt lgkmcnt(0)
	s_setprio 1
	s_waitcnt lgkmcnt(0)
	v_mfma_f32_16x16x32_bf16 v[6:9], v[164:167], v[204:207], v[58:61]
	v_mfma_f32_16x16x32_bf16 v[10:13], v[188:191], v[204:207], v[50:53]
	v_mfma_f32_16x16x32_bf16 v[2:5], v[164:167], v[14:17], v[62:65]
	v_mfma_f32_16x16x32_bf16 v[18:21], v[184:187], v[216:219], v[6:9]
	v_mfma_f32_16x16x32_bf16 v[6:9], v[188:191], v[14:17], v[54:57]
	v_mfma_f32_16x16x32_bf16 v[22:25], v[192:195], v[216:219], v[10:13]
	v_mfma_f32_16x16x32_bf16 v[10:13], v[196:199], v[14:17], v[46:49]
	v_mfma_f32_16x16x32_bf16 v[14:17], v[224:227], v[14:17], v[38:41]
	v_mfma_f32_16x16x32_bf16 v[2:5], v[184:187], v[30:33], v[2:5]
	v_mfma_f32_16x16x32_bf16 v[6:9], v[192:195], v[30:33], v[6:9]
	v_mfma_f32_16x16x32_bf16 v[10:13], v[220:223], v[30:33], v[10:13]
	v_mfma_f32_16x16x32_bf16 v[26:29], v[196:199], v[204:207], v[42:45]
	v_mfma_f32_16x16x32_bf16 v[14:17], v[232:235], v[30:33], v[14:17]
	v_mfma_f32_16x16x32_bf16 v[30:33], v[224:227], v[204:207], v[34:37]
	v_mfma_f32_16x16x32_bf16 v[26:29], v[220:223], v[216:219], v[26:29]
	v_mfma_f32_16x16x32_bf16 v[30:33], v[232:235], v[216:219], v[30:33]
	s_setprio 0
	s_setprio 1
	v_mfma_f32_16x16x32_bf16 v[38:41], v[164:167], v[240:243], v[152:155]
	v_mfma_f32_16x16x32_bf16 v[42:45], v[188:191], v[240:243], v[160:163]
	v_mfma_f32_16x16x32_bf16 v[46:49], v[196:199], v[240:243], v[228:231]
	v_mfma_f32_16x16x32_bf16 v[34:37], v[164:167], v[140:143], v[148:151]
	v_mfma_f32_16x16x32_bf16 v[50:53], v[184:187], v[144:147], v[38:41]
	v_mfma_f32_16x16x32_bf16 v[38:41], v[188:191], v[140:143], v[156:159]
	v_mfma_f32_16x16x32_bf16 v[54:57], v[192:195], v[144:147], v[42:45]
	v_mfma_f32_16x16x32_bf16 v[42:45], v[196:199], v[140:143], v[208:211]
	v_mfma_f32_16x16x32_bf16 v[58:61], v[220:223], v[144:147], v[46:49]
	v_mfma_f32_16x16x32_bf16 v[46:49], v[224:227], v[140:143], v[212:215]
	v_mfma_f32_16x16x32_bf16 v[62:65], v[224:227], v[240:243], v[200:203]
	v_mfma_f32_16x16x32_bf16 v[34:37], v[184:187], v[236:239], v[34:37]
	v_mfma_f32_16x16x32_bf16 v[38:41], v[192:195], v[236:239], v[38:41]
	v_mfma_f32_16x16x32_bf16 v[42:45], v[220:223], v[236:239], v[42:45]
	v_mfma_f32_16x16x32_bf16 v[46:49], v[232:235], v[236:239], v[46:49]
	v_mfma_f32_16x16x32_bf16 v[62:65], v[232:235], v[144:147], v[62:65]
	s_setprio 0
	v_readlane_b32 s4, v245, 33
	v_readlane_b32 s5, v245, 34
	s_and_b64 vcc, exec, s[4:5]
	s_barrier
	s_cbranch_vccz .LBB0_101
	s_barrier

; #define LDA(dst, b, h) for (int m = 0; m < 4; ++m) for (int k = 0; k < 2; ++k) \
;     dst[m][k] = *reinterpret_cast<const bf16x8*>((char*)SA(b, h) + lds_byte(wr * 64 + m * 16 + fr, k * 32 + fq * 8))
; #define LDB(dst, b, h) for (int n = 0; n < 2; ++n) for (int k = 0; k < 2; ++k) \
;     dst[n][k] = *reinterpret_cast<const bf16x8*>((char*)SB(b, h) + lds_byte(wc * 32 + n * 16 + fr, k * 32 + fq * 8))
; #define MMA(ai, bj, At, Bt_) do { __builtin_amdgcn_s_setprio(1); \
;     for (int m = 0; m < 4; ++m) for (int n = 0; n < 2; ++n) for (int k = 0; k < 2; ++k) \
;       acc[ai][bj][m][n] = __builtin_amdgcn_mfma_f32_16x16x32_bf16(At[m][k], Bt_[n][k], acc[ai][bj][m][n], 0, 0, 0); \
;     __builtin_amdgcn_s_setprio(0); } while (0)
; #define WAIT_L(n) asm volatile("s_waitcnt lgkmcnt(" #n ")" ::: "memory")
; #define BAR __builtin_amdgcn_s_barrier()
; #define SCHED __builtin_amdgcn_sched_barrier(0)
;     ...
;       LDB(B0, 0, 0); SCHED; LDA(At, 0, 0); STAGE(SA(1, 1), A, brow + HALF, t + 1);
;       WAIT_L(8); BAR; WAIT_L(0); MMA(0, 0, At, B0); BAR; SCHED;
;       LDB(B1, 0, 1); STAGE(SB(0, 0), Bt, bcol, t + 2);
;       BAR; WAIT_L(0); MMA(0, 1, At, B1); BAR;
;       LDA(At, 0, 1); STAGE(SA(0, 0), A, brow, t + 2);
;       BAR; WAIT_L(0); MMA(1, 0, At, B0); BAR; SCHED;
.LBB0_155:
	v_add_u32_e32 v143, s2, v142
	ds_read_b128 v[146:149], v143
	ds_read_b128 v[150:153], v143 offset:1024
	ds_read_b128 v[154:157], v143 offset:2048
	ds_read_b128 v[158:161], v143 offset:3072
	s_add_u32 s40, s30, s10
	s_addc_u32 s41, s31, s11
	s_add_u32 s42, s40, 0x80080
	s_addc_u32 s43, s41, 0
	s_add_i32 s39, s24, 0xc000
	ds_read_b128 v[162:165], v133
	ds_read_b128 v[184:187], v133 offset:1024
	ds_read_b128 v[188:191], v134
	ds_read_b128 v[192:195], v134 offset:1024
	ds_read_b128 v[196:199], v137
	ds_read_b128 v[200:203], v137 offset:1024
	ds_read_b128 v[204:207], v139
	ds_read_b128 v[208:211], v139 offset:1024
	s_mov_b32 m0, s39
	v_lshl_add_u64 v[144:145], s[42:43], 0, v[0:1]
	s_add_i32 s38, s24, 0xe000
	global_load_lds_dwordx4 v[144:145], off
	v_lshl_add_u64 v[144:145], s[42:43], 0, v[140:141]
	s_mov_b32 m0, s38
	s_nop 0
	global_load_lds_dwordx4 v[144:145], off
	s_barrier
	s_waitcnt lgkmcnt(0)
	s_waitcnt lgkmcnt(0)
	v_mfma_f32_16x16x32_bf16 v[126:129], v[162:165], v[146:149], v[126:129]
	v_mfma_f32_16x16x32_bf16 v[122:125], v[162:165], v[154:157], v[122:125]
	v_mfma_f32_16x16x32_bf16 v[118:121], v[188:191], v[146:149], v[118:121]
	v_mfma_f32_16x16x32_bf16 v[114:117], v[188:191], v[154:157], v[114:117]
	v_mfma_f32_16x16x32_bf16 v[110:113], v[196:199], v[146:149], v[110:113]
	v_mfma_f32_16x16x32_bf16 v[106:109], v[196:199], v[154:157], v[106:109]
	v_mfma_f32_16x16x32_bf16 v[102:105], v[204:207], v[146:149], v[102:105]
	v_mfma_f32_16x16x32_bf16 v[98:101], v[204:207], v[154:157], v[98:101]
	v_mfma_f32_16x16x32_bf16 v[126:129], v[184:187], v[150:153], v[126:129]
	v_mfma_f32_16x16x32_bf16 v[122:125], v[184:187], v[158:161], v[122:125]
	v_mfma_f32_16x16x32_bf16 v[118:121], v[192:195], v[150:153], v[118:121]
	v_mfma_f32_16x16x32_bf16 v[114:117], v[192:195], v[158:161], v[114:117]
	v_mfma_f32_16x16x32_bf16 v[110:113], v[200:203], v[150:153], v[110:113]
	v_mfma_f32_16x16x32_bf16 v[106:109], v[200:203], v[158:161], v[106:109]
	v_mfma_f32_16x16x32_bf16 v[102:105], v[208:211], v[150:153], v[102:105]
	v_mfma_f32_16x16x32_bf16 v[98:101], v[208:211], v[158:161], v[98:101]
	s_barrier
	s_add_u32 s42, s34, s10
	s_addc_u32 s43, s35, s11
	s_add_u32 s44, s42, 0x100
	v_add_u32_e32 v144, s76, v142
	s_addc_u32 s45, s43, 0
	s_mov_b32 m0, s25
	ds_read_b128 v[212:215], v144
	ds_read_b128 v[216:219], v144 offset:1024
	ds_read_b128 v[220:223], v144 offset:2048
	ds_read_b128 v[224:227], v144 offset:3072
	s_nop 0
	v_lshl_add_u64 v[166:167], s[44:45], 0, v[0:1]
	global_load_lds_dwordx4 v[166:167], off
	v_lshl_add_u64 v[166:167], s[44:45], 0, v[140:141]
	s_mov_b32 m0, s26
	s_nop 0
	global_load_lds_dwordx4 v[166:167], off
	s_barrier
	s_waitcnt lgkmcnt(0)
	s_waitcnt lgkmcnt(0)
	v_mfma_f32_16x16x32_bf16 v[94:97], v[162:165], v[212:215], v[94:97]
	v_mfma_f32_16x16x32_bf16 v[90:93], v[162:165], v[220:223], v[90:93]
	v_mfma_f32_16x16x32_bf16 v[86:89], v[188:191], v[212:215], v[86:89]
	v_mfma_f32_16x16x32_bf16 v[82:85], v[188:191], v[220:223], v[82:85]
	v_mfma_f32_16x16x32_bf16 v[78:81], v[196:199], v[212:215], v[78:81]
	v_mfma_f32_16x16x32_bf16 v[74:77], v[196:199], v[220:223], v[74:77]
	v_mfma_f32_16x16x32_bf16 v[70:73], v[204:207], v[212:215], v[70:73]
	v_mfma_f32_16x16x32_bf16 v[66:69], v[204:207], v[220:223], v[66:69]
	v_mfma_f32_16x16x32_bf16 v[94:97], v[184:187], v[216:219], v[94:97]
	v_mfma_f32_16x16x32_bf16 v[90:93], v[184:187], v[224:227], v[90:93]
	v_mfma_f32_16x16x32_bf16 v[86:89], v[192:195], v[216:219], v[86:89]
	v_mfma_f32_16x16x32_bf16 v[82:85], v[192:195], v[224:227], v[82:85]
	v_mfma_f32_16x16x32_bf16 v[78:81], v[200:203], v[216:219], v[78:81]
	v_mfma_f32_16x16x32_bf16 v[74:77], v[200:203], v[224:227], v[74:77]
	v_mfma_f32_16x16x32_bf16 v[70:73], v[208:211], v[216:219], v[70:73]
	v_mfma_f32_16x16x32_bf16 v[66:69], v[208:211], v[224:227], v[66:69]
	s_add_u32 s44, s40, 0x100
	s_addc_u32 s45, s41, 0
	s_mov_b32 m0, s24
	s_barrier
	ds_read_b128 v[162:165], v133 offset:16384
	ds_read_b128 v[184:187], v133 offset:17408
	ds_read_b128 v[188:191], v134 offset:16384
	ds_read_b128 v[192:195], v134 offset:17408
	ds_read_b128 v[196:199], v137 offset:16384
	ds_read_b128 v[200:203], v137 offset:17408
	ds_read_b128 v[204:207], v139 offset:16384
	ds_read_b128 v[208:211], v139 offset:17408
	s_nop 0
	v_lshl_add_u64 v[166:167], s[44:45], 0, v[0:1]
	global_load_lds_dwordx4 v[166:167], off
	v_lshl_add_u64 v[166:167], s[44:45], 0, v[140:141]
	s_mov_b32 m0, s9
	s_nop 0
	global_load_lds_dwordx4 v[166:167], off
	s_barrier
	s_waitcnt lgkmcnt(0)
	s_waitcnt lgkmcnt(0)
	v_mfma_f32_16x16x32_bf16 v[62:65], v[162:165], v[146:149], v[62:65]
	v_mfma_f32_16x16x32_bf16 v[58:61], v[162:165], v[154:157], v[58:61]
	v_mfma_f32_16x16x32_bf16 v[54:57], v[188:191], v[146:149], v[54:57]
	v_mfma_f32_16x16x32_bf16 v[50:53], v[188:191], v[154:157], v[50:53]
	v_mfma_f32_16x16x32_bf16 v[46:49], v[196:199], v[146:149], v[46:49]
	v_mfma_f32_16x16x32_bf16 v[42:45], v[196:199], v[154:157], v[42:45]
	v_mfma_f32_16x16x32_bf16 v[38:41], v[204:207], v[146:149], v[38:41]
	v_mfma_f32_16x16x32_bf16 v[34:37], v[204:207], v[154:157], v[34:37]
	v_mfma_f32_16x16x32_bf16 v[62:65], v[184:187], v[150:153], v[62:65]
	v_mfma_f32_16x16x32_bf16 v[58:61], v[184:187], v[158:161], v[58:61]
	v_mfma_f32_16x16x32_bf16 v[54:57], v[192:195], v[150:153], v[54:57]
	v_mfma_f32_16x16x32_bf16 v[50:53], v[192:195], v[158:161], v[50:53]
	v_mfma_f32_16x16x32_bf16 v[46:49], v[200:203], v[150:153], v[46:49]
	v_mfma_f32_16x16x32_bf16 v[42:45], v[200:203], v[158:161], v[42:45]
	v_mfma_f32_16x16x32_bf16 v[38:41], v[208:211], v[150:153], v[38:41]
	v_mfma_f32_16x16x32_bf16 v[34:37], v[208:211], v[158:161], v[34:37]
	s_barrier
; #define LDA(dst, b, h) for (int m = 0; m < 4; ++m) for (int k = 0; k < 2; ++k) \
;     dst[m][k] = *reinterpret_cast<const bf16x8*>((char*)SA(b, h) + lds_byte(wr * 64 + m * 16 + fr, k * 32 + fq * 8))
; #define LDB(dst, b, h) for (int n = 0; n < 2; ++n) for (int k = 0; k < 2; ++k) \
;     dst[n][k] = *reinterpret_cast<const bf16x8*>((char*)SB(b, h) + lds_byte(wc * 32 + n * 16 + fr, k * 32 + fq * 8))
; #define MMA(ai, bj, At, Bt_) do { __builtin_amdgcn_s_setprio(1); \
;     for (int m = 0; m < 4; ++m) for (int n = 0; n < 2; ++n) for (int k = 0; k < 2; ++k) \
;       acc[ai][bj][m][n] = __builtin_amdgcn_mfma_f32_16x16x32_bf16(At[m][k], Bt_[n][k], acc[ai][bj][m][n], 0, 0, 0); \
;     __builtin_amdgcn_s_setprio(0); } while (0)
; #define WAIT_V(n) asm volatile("s_waitcnt vmcnt(" #n ")" ::: "memory")
; #define WAIT_L(n) asm volatile("s_waitcnt lgkmcnt(" #n ")" ::: "memory")
; #define BAR __builtin_amdgcn_s_barrier()
; #define SCHED __builtin_amdgcn_sched_barrier(0)
;     ...
;       STAGE(SB(0, 1), Bt, bcol + HALF, t + 2);
;       WAIT_V(6); BAR; MMA(1, 1, At, B1); BAR;
;       LDB(B0, 1, 0); SCHED; LDA(At, 1, 0); STAGE(SA(0, 1), A, brow + HALF, t + 2);
;       WAIT_L(8); BAR; WAIT_L(0); MMA(0, 0, At, B0); BAR; SCHED;
;       LDB(B1, 1, 1); STAGE(SB(1, 0), Bt, bcol, t + 3);
;       BAR; WAIT_L(0); MMA(0, 1, At, B1); BAR;
;       LDA(At, 1, 1); STAGE(SA(1, 0), A, brow, t + 3);
	s_add_u32 s44, s42, 0x80100
	s_addc_u32 s45, s43, 0
	s_mov_b32 m0, s27
	s_nop 0
	v_lshl_add_u64 v[146:147], s[44:45], 0, v[0:1]
	global_load_lds_dwordx4 v[146:147], off
	v_lshl_add_u64 v[146:147], s[44:45], 0, v[140:141]
	s_mov_b32 m0, s28
	s_nop 0
	global_load_lds_dwordx4 v[146:147], off
	s_waitcnt vmcnt(6)
	s_barrier
	v_mfma_f32_16x16x32_bf16 v[30:33], v[162:165], v[212:215], v[30:33]
	v_mfma_f32_16x16x32_bf16 v[26:29], v[162:165], v[220:223], v[26:29]
	v_mfma_f32_16x16x32_bf16 v[22:25], v[188:191], v[212:215], v[22:25]
	v_mfma_f32_16x16x32_bf16 v[18:21], v[188:191], v[220:223], v[18:21]
	v_mfma_f32_16x16x32_bf16 v[14:17], v[196:199], v[212:215], v[14:17]
	v_mfma_f32_16x16x32_bf16 v[10:13], v[196:199], v[220:223], v[10:13]
	v_mfma_f32_16x16x32_bf16 v[6:9], v[204:207], v[212:215], v[6:9]
	v_mfma_f32_16x16x32_bf16 v[2:5], v[204:207], v[220:223], v[2:5]
	v_mfma_f32_16x16x32_bf16 v[30:33], v[184:187], v[216:219], v[30:33]
	v_mfma_f32_16x16x32_bf16 v[26:29], v[184:187], v[224:227], v[26:29]
	v_mfma_f32_16x16x32_bf16 v[22:25], v[192:195], v[216:219], v[22:25]
	v_mfma_f32_16x16x32_bf16 v[18:21], v[192:195], v[224:227], v[18:21]
	v_mfma_f32_16x16x32_bf16 v[14:17], v[200:203], v[216:219], v[14:17]
	v_mfma_f32_16x16x32_bf16 v[10:13], v[200:203], v[224:227], v[10:13]
	v_mfma_f32_16x16x32_bf16 v[6:9], v[208:211], v[216:219], v[6:9]
	v_mfma_f32_16x16x32_bf16 v[2:5], v[208:211], v[224:227], v[2:5]
	v_add_u32_e32 v145, s77, v142
	s_barrier
	ds_read_b128 v[148:151], v145
	ds_read_b128 v[152:155], v145 offset:1024
	ds_read_b128 v[156:159], v145 offset:2048
	ds_read_b128 v[160:163], v145 offset:3072
	s_add_u32 s44, s40, 0x80100
	s_addc_u32 s45, s41, 0
	s_mov_b32 m0, s7
	ds_read_b128 v[164:167], v133 offset:32768
	ds_read_b128 v[184:187], v133 offset:33792
	ds_read_b128 v[188:191], v134 offset:32768
	ds_read_b128 v[192:195], v134 offset:33792
	ds_read_b128 v[196:199], v137 offset:32768
	ds_read_b128 v[200:203], v137 offset:33792
	ds_read_b128 v[204:207], v139 offset:32768
	ds_read_b128 v[208:211], v139 offset:33792
	s_nop 0
	v_lshl_add_u64 v[146:147], s[44:45], 0, v[0:1]
	global_load_lds_dwordx4 v[146:147], off
	v_lshl_add_u64 v[146:147], s[44:45], 0, v[140:141]
	s_mov_b32 m0, s29
	s_nop 0
	global_load_lds_dwordx4 v[146:147], off
	s_barrier
	s_waitcnt lgkmcnt(0)
	s_waitcnt lgkmcnt(0)
	v_mfma_f32_16x16x32_bf16 v[126:129], v[164:167], v[148:151], v[126:129]
	v_mfma_f32_16x16x32_bf16 v[122:125], v[164:167], v[156:159], v[122:125]
	v_mfma_f32_16x16x32_bf16 v[118:121], v[188:191], v[148:151], v[118:121]
	v_mfma_f32_16x16x32_bf16 v[114:117], v[188:191], v[156:159], v[114:117]
	v_mfma_f32_16x16x32_bf16 v[110:113], v[196:199], v[148:151], v[110:113]
	v_mfma_f32_16x16x32_bf16 v[106:109], v[196:199], v[156:159], v[106:109]
	v_mfma_f32_16x16x32_bf16 v[102:105], v[204:207], v[148:151], v[102:105]
	v_mfma_f32_16x16x32_bf16 v[98:101], v[204:207], v[156:159], v[98:101]
	v_mfma_f32_16x16x32_bf16 v[126:129], v[184:187], v[152:155], v[126:129]
	v_mfma_f32_16x16x32_bf16 v[122:125], v[184:187], v[160:163], v[122:125]
	v_mfma_f32_16x16x32_bf16 v[118:121], v[192:195], v[152:155], v[118:121]
	v_mfma_f32_16x16x32_bf16 v[114:117], v[192:195], v[160:163], v[114:117]
	v_mfma_f32_16x16x32_bf16 v[110:113], v[200:203], v[152:155], v[110:113]
	v_mfma_f32_16x16x32_bf16 v[106:109], v[200:203], v[160:163], v[106:109]
	v_mfma_f32_16x16x32_bf16 v[102:105], v[208:211], v[152:155], v[102:105]
	v_mfma_f32_16x16x32_bf16 v[98:101], v[208:211], v[160:163], v[98:101]
	s_barrier
	s_add_u32 s44, s42, 0x180
	v_add_u32_e32 v146, s78, v142
	s_addc_u32 s45, s43, 0
	s_mov_b32 m0, s12
	ds_read_b128 v[212:215], v146
	ds_read_b128 v[216:219], v146 offset:1024
	ds_read_b128 v[220:223], v146 offset:2048
	ds_read_b128 v[224:227], v146 offset:3072
	s_nop 0
	v_lshl_add_u64 v[228:229], s[44:45], 0, v[0:1]
	global_load_lds_dwordx4 v[228:229], off
	v_lshl_add_u64 v[228:229], s[44:45], 0, v[140:141]
	s_mov_b32 m0, s13
	s_nop 0
	global_load_lds_dwordx4 v[228:229], off
	s_barrier
	s_waitcnt lgkmcnt(0)
	s_waitcnt lgkmcnt(0)
	v_mfma_f32_16x16x32_bf16 v[94:97], v[164:167], v[212:215], v[94:97]
	v_mfma_f32_16x16x32_bf16 v[90:93], v[164:167], v[220:223], v[90:93]
	v_mfma_f32_16x16x32_bf16 v[86:89], v[188:191], v[212:215], v[86:89]
	v_mfma_f32_16x16x32_bf16 v[82:85], v[188:191], v[220:223], v[82:85]
	v_mfma_f32_16x16x32_bf16 v[78:81], v[196:199], v[212:215], v[78:81]
	v_mfma_f32_16x16x32_bf16 v[74:77], v[196:199], v[220:223], v[74:77]
	v_mfma_f32_16x16x32_bf16 v[70:73], v[204:207], v[212:215], v[70:73]
	v_mfma_f32_16x16x32_bf16 v[66:69], v[204:207], v[220:223], v[66:69]
	v_mfma_f32_16x16x32_bf16 v[94:97], v[184:187], v[216:219], v[94:97]
	v_mfma_f32_16x16x32_bf16 v[90:93], v[184:187], v[224:227], v[90:93]
	v_mfma_f32_16x16x32_bf16 v[86:89], v[192:195], v[216:219], v[86:89]
	v_mfma_f32_16x16x32_bf16 v[82:85], v[192:195], v[224:227], v[82:85]
	v_mfma_f32_16x16x32_bf16 v[78:81], v[200:203], v[216:219], v[78:81]
	v_mfma_f32_16x16x32_bf16 v[74:77], v[200:203], v[224:227], v[74:77]
	v_mfma_f32_16x16x32_bf16 v[70:73], v[208:211], v[216:219], v[70:73]
	v_mfma_f32_16x16x32_bf16 v[66:69], v[208:211], v[224:227], v[66:69]
	s_add_u32 s40, s40, 0x180
	s_addc_u32 s41, s41, 0
	s_mov_b32 m0, s14
	s_barrier
	ds_read_b128 v[164:167], v133 offset:49152
	ds_read_b128 v[184:187], v133 offset:50176
	ds_read_b128 v[188:191], v134 offset:49152
	ds_read_b128 v[192:195], v134 offset:50176
	ds_read_b128 v[196:199], v137 offset:49152
	ds_read_b128 v[200:203], v137 offset:50176
	ds_read_b128 v[204:207], v139 offset:49152
	ds_read_b128 v[208:211], v139 offset:50176
	s_nop 0
	v_lshl_add_u64 v[228:229], s[40:41], 0, v[0:1]
	global_load_lds_dwordx4 v[228:229], off
	v_lshl_add_u64 v[228:229], s[40:41], 0, v[140:141]
	s_mov_b32 m0, s15
	s_nop 0
	global_load_lds_dwordx4 v[228:229], off
	s_barrier
; #define LDA(dst, b, h) for (int m = 0; m < 4; ++m) for (int k = 0; k < 2; ++k) \
;     dst[m][k] = *reinterpret_cast<const bf16x8*>((char*)SA(b, h) + lds_byte(wr * 64 + m * 16 + fr, k * 32 + fq * 8))
; #define LDB(dst, b, h) for (int n = 0; n < 2; ++n) for (int k = 0; k < 2; ++k) \
;     dst[n][k] = *reinterpret_cast<const bf16x8*>((char*)SB(b, h) + lds_byte(wc * 32 + n * 16 + fr, k * 32 + fq * 8))
; #define MMA(ai, bj, At, Bt_) do { __builtin_amdgcn_s_setprio(1); \
;     for (int m = 0; m < 4; ++m) for (int n = 0; n < 2; ++n) for (int k = 0; k < 2; ++k) \
;       acc[ai][bj][m][n] = __builtin_amdgcn_mfma_f32_16x16x32_bf16(At[m][k], Bt_[n][k], acc[ai][bj][m][n], 0, 0, 0); \
;     __builtin_amdgcn_s_setprio(0); } while (0)
; #define WAIT_V(n) asm volatile("s_waitcnt vmcnt(" #n ")" ::: "memory")
; #define WAIT_L(n) asm volatile("s_waitcnt lgkmcnt(" #n ")" ::: "memory")
; #define BAR __builtin_amdgcn_s_barrier()
; #define SCHED __builtin_amdgcn_sched_barrier(0)
;     ...
;       BAR; WAIT_L(0); MMA(1, 0, At, B0); BAR; SCHED;
;       STAGE(SB(1, 1), Bt, bcol + HALF, t + 3);
;       WAIT_V(6); BAR; MMA(1, 1, At, B1); BAR;
;     }
;     { LDB(B0, 0, 0); LDA(At, 0, 0); STAGE(SA(1, 1), A, brow + HALF, nt - 1);
;       BAR; WAIT_L(0); MMA(0, 0, At, B0); BAR;
;       LDB(B1, 0, 1); BAR; WAIT_L(0); MMA(0, 1, At, B1); BAR;
	s_waitcnt lgkmcnt(0)
	s_waitcnt lgkmcnt(0)
	v_mfma_f32_16x16x32_bf16 v[62:65], v[164:167], v[148:151], v[62:65]
	v_mfma_f32_16x16x32_bf16 v[58:61], v[164:167], v[156:159], v[58:61]
	v_mfma_f32_16x16x32_bf16 v[54:57], v[188:191], v[148:151], v[54:57]
	v_mfma_f32_16x16x32_bf16 v[50:53], v[188:191], v[156:159], v[50:53]
	v_mfma_f32_16x16x32_bf16 v[46:49], v[196:199], v[148:151], v[46:49]
	v_mfma_f32_16x16x32_bf16 v[42:45], v[196:199], v[156:159], v[42:45]
	v_mfma_f32_16x16x32_bf16 v[38:41], v[204:207], v[148:151], v[38:41]
	v_mfma_f32_16x16x32_bf16 v[34:37], v[204:207], v[156:159], v[34:37]
	v_mfma_f32_16x16x32_bf16 v[62:65], v[184:187], v[152:155], v[62:65]
	v_mfma_f32_16x16x32_bf16 v[58:61], v[184:187], v[160:163], v[58:61]
	v_mfma_f32_16x16x32_bf16 v[54:57], v[192:195], v[152:155], v[54:57]
	v_mfma_f32_16x16x32_bf16 v[50:53], v[192:195], v[160:163], v[50:53]
	v_mfma_f32_16x16x32_bf16 v[46:49], v[200:203], v[152:155], v[46:49]
	v_mfma_f32_16x16x32_bf16 v[42:45], v[200:203], v[160:163], v[42:45]
	v_mfma_f32_16x16x32_bf16 v[38:41], v[208:211], v[152:155], v[38:41]
	v_mfma_f32_16x16x32_bf16 v[34:37], v[208:211], v[160:163], v[34:37]
	s_barrier
	s_add_u32 s40, s42, 0x80180
	s_addc_u32 s41, s43, 0
	s_mov_b32 m0, s16
	s_nop 0
	v_lshl_add_u64 v[148:149], s[40:41], 0, v[0:1]
	global_load_lds_dwordx4 v[148:149], off
	v_lshl_add_u64 v[148:149], s[40:41], 0, v[140:141]
	s_mov_b32 m0, s17
	s_nop 0
	global_load_lds_dwordx4 v[148:149], off
	s_waitcnt vmcnt(6)
	s_barrier
	v_mfma_f32_16x16x32_bf16 v[30:33], v[164:167], v[212:215], v[30:33]
	v_mfma_f32_16x16x32_bf16 v[26:29], v[164:167], v[220:223], v[26:29]
	v_mfma_f32_16x16x32_bf16 v[22:25], v[188:191], v[212:215], v[22:25]
	v_mfma_f32_16x16x32_bf16 v[18:21], v[188:191], v[220:223], v[18:21]
	v_mfma_f32_16x16x32_bf16 v[14:17], v[196:199], v[212:215], v[14:17]
	v_mfma_f32_16x16x32_bf16 v[10:13], v[196:199], v[220:223], v[10:13]
	v_mfma_f32_16x16x32_bf16 v[6:9], v[204:207], v[212:215], v[6:9]
	v_mfma_f32_16x16x32_bf16 v[2:5], v[204:207], v[220:223], v[2:5]
	v_mfma_f32_16x16x32_bf16 v[30:33], v[184:187], v[216:219], v[30:33]
	v_mfma_f32_16x16x32_bf16 v[26:29], v[184:187], v[224:227], v[26:29]
	v_mfma_f32_16x16x32_bf16 v[22:25], v[192:195], v[216:219], v[22:25]
	v_mfma_f32_16x16x32_bf16 v[18:21], v[192:195], v[224:227], v[18:21]
	v_mfma_f32_16x16x32_bf16 v[14:17], v[200:203], v[216:219], v[14:17]
	v_mfma_f32_16x16x32_bf16 v[10:13], v[200:203], v[224:227], v[10:13]
	v_mfma_f32_16x16x32_bf16 v[6:9], v[208:211], v[216:219], v[6:9]
	v_mfma_f32_16x16x32_bf16 v[2:5], v[208:211], v[224:227], v[2:5]
	s_add_i32 s37, s37, 2
	s_add_u32 s10, s10, 0x100
	s_addc_u32 s11, s11, 0
	s_cmp_gt_u32 s37, 27
	s_barrier
	s_cbranch_scc0 .LBB0_155
	s_add_u32 s4, s4, 0xf80
	s_addc_u32 s5, s5, 0
	s_mov_b32 m0, s39
	ds_read_b128 v[148:151], v143
	ds_read_b128 v[152:155], v143 offset:1024
	ds_read_b128 v[156:159], v143 offset:2048
	ds_read_b128 v[160:163], v143 offset:3072
	ds_read_b128 v[164:167], v133
	ds_read_b128 v[184:187], v133 offset:1024
	ds_read_b128 v[188:191], v134
	ds_read_b128 v[192:195], v134 offset:1024
	ds_read_b128 v[196:199], v137
	ds_read_b128 v[200:203], v137 offset:1024
	ds_read_b128 v[204:207], v139
	ds_read_b128 v[208:211], v139 offset:1024
	s_nop 0
	v_lshl_add_u64 v[142:143], s[4:5], 0, v[0:1]
	global_load_lds_dwordx4 v[142:143], off
	v_lshl_add_u64 v[140:141], s[4:5], 0, v[140:141]
	s_mov_b32 m0, s38
	s_nop 0
	global_load_lds_dwordx4 v[140:141], off
	s_barrier
	s_waitcnt lgkmcnt(0)
	s_setprio 1
	s_waitcnt lgkmcnt(0)
	v_mfma_f32_16x16x32_bf16 v[126:129], v[164:167], v[148:151], v[126:129]
	v_mfma_f32_16x16x32_bf16 v[118:121], v[188:191], v[148:151], v[118:121]
	v_mfma_f32_16x16x32_bf16 v[110:113], v[196:199], v[148:151], v[110:113]
	v_mfma_f32_16x16x32_bf16 v[102:105], v[204:207], v[148:151], v[102:105]
	v_mfma_f32_16x16x32_bf16 v[126:129], v[184:187], v[152:155], v[126:129]
	v_mfma_f32_16x16x32_bf16 v[122:125], v[164:167], v[156:159], v[122:125]
	v_mfma_f32_16x16x32_bf16 v[118:121], v[192:195], v[152:155], v[118:121]
	v_mfma_f32_16x16x32_bf16 v[114:117], v[188:191], v[156:159], v[114:117]
	v_mfma_f32_16x16x32_bf16 v[110:113], v[200:203], v[152:155], v[110:113]
	v_mfma_f32_16x16x32_bf16 v[106:109], v[196:199], v[156:159], v[106:109]
	v_mfma_f32_16x16x32_bf16 v[102:105], v[208:211], v[152:155], v[102:105]
	v_mfma_f32_16x16x32_bf16 v[98:101], v[204:207], v[156:159], v[98:101]
	v_mfma_f32_16x16x32_bf16 v[140:143], v[184:187], v[160:163], v[122:125]
	v_mfma_f32_16x16x32_bf16 v[212:215], v[192:195], v[160:163], v[114:117]
	v_mfma_f32_16x16x32_bf16 v[216:219], v[200:203], v[160:163], v[106:109]
	v_mfma_f32_16x16x32_bf16 v[220:223], v[208:211], v[160:163], v[98:101]
	s_setprio 0
	s_barrier
	s_nop 1
	ds_read_b128 v[98:101], v144
	ds_read_b128 v[106:109], v144 offset:1024
	ds_read_b128 v[114:117], v144 offset:2048
	ds_read_b128 v[122:125], v144 offset:3072
	s_barrier
	s_waitcnt lgkmcnt(0)
	s_setprio 1
	s_waitcnt lgkmcnt(0)
	v_mfma_f32_16x16x32_bf16 v[94:97], v[164:167], v[98:101], v[94:97]
	v_mfma_f32_16x16x32_bf16 v[86:89], v[188:191], v[98:101], v[86:89]
	v_mfma_f32_16x16x32_bf16 v[78:81], v[196:199], v[98:101], v[78:81]
	v_mfma_f32_16x16x32_bf16 v[70:73], v[204:207], v[98:101], v[70:73]
	v_mfma_f32_16x16x32_bf16 v[94:97], v[184:187], v[106:109], v[94:97]
	v_mfma_f32_16x16x32_bf16 v[90:93], v[164:167], v[114:117], v[90:93]
	v_mfma_f32_16x16x32_bf16 v[86:89], v[192:195], v[106:109], v[86:89]
	v_mfma_f32_16x16x32_bf16 v[82:85], v[188:191], v[114:117], v[82:85]
	v_mfma_f32_16x16x32_bf16 v[78:81], v[200:203], v[106:109], v[78:81]
	v_mfma_f32_16x16x32_bf16 v[74:77], v[196:199], v[114:117], v[74:77]
	v_mfma_f32_16x16x32_bf16 v[70:73], v[208:211], v[106:109], v[70:73]
	v_mfma_f32_16x16x32_bf16 v[66:69], v[204:207], v[114:117], v[66:69]
	v_mfma_f32_16x16x32_bf16 v[164:167], v[184:187], v[122:125], v[90:93]
	v_mfma_f32_16x16x32_bf16 v[184:187], v[192:195], v[122:125], v[82:85]
	v_mfma_f32_16x16x32_bf16 v[188:191], v[200:203], v[122:125], v[74:77]
	v_mfma_f32_16x16x32_bf16 v[192:195], v[208:211], v[122:125], v[66:69]
	s_setprio 0
	s_barrier
; #define LDA(dst, b, h) for (int m = 0; m < 4; ++m) for (int k = 0; k < 2; ++k) \
;     dst[m][k] = *reinterpret_cast<const bf16x8*>((char*)SA(b, h) + lds_byte(wr * 64 + m * 16 + fr, k * 32 + fq * 8))
; #define LDB(dst, b, h) for (int n = 0; n < 2; ++n) for (int k = 0; k < 2; ++k) \
;     dst[n][k] = *reinterpret_cast<const bf16x8*>((char*)SB(b, h) + lds_byte(wc * 32 + n * 16 + fr, k * 32 + fq * 8))
; #define MMA(ai, bj, At, Bt_) do { __builtin_amdgcn_s_setprio(1); \
;     for (int m = 0; m < 4; ++m) for (int n = 0; n < 2; ++n) for (int k = 0; k < 2; ++k) \
;       acc[ai][bj][m][n] = __builtin_amdgcn_mfma_f32_16x16x32_bf16(At[m][k], Bt_[n][k], acc[ai][bj][m][n], 0, 0, 0); \
;     __builtin_amdgcn_s_setprio(0); } while (0)
; #define WAIT_V(n) asm volatile("s_waitcnt vmcnt(" #n ")" ::: "memory")
; #define WAIT_L(n) asm volatile("s_waitcnt lgkmcnt(" #n ")" ::: "memory")
; #define BAR __builtin_amdgcn_s_barrier()
;     ...
;       LDA(At, 0, 1); WAIT_V(4); BAR; WAIT_L(0); MMA(1, 0, At, B0); MMA(1, 1, At, B1); BAR; }
;     { LDB(B0, 1, 0); LDA(At, 1, 0); WAIT_V(2); BAR; WAIT_L(0); MMA(0, 0, At, B0); BAR;
	s_nop 1
	ds_read_b128 v[66:69], v133 offset:16384
	ds_read_b128 v[74:77], v133 offset:17408
	ds_read_b128 v[82:85], v134 offset:16384
	ds_read_b128 v[90:93], v134 offset:17408
	ds_read_b128 v[196:199], v137 offset:16384
	ds_read_b128 v[200:203], v137 offset:17408
	ds_read_b128 v[204:207], v139 offset:16384
	ds_read_b128 v[208:211], v139 offset:17408
	s_waitcnt vmcnt(4)
	s_barrier
	s_waitcnt lgkmcnt(0)
	s_setprio 1
	s_waitcnt lgkmcnt(0)
	v_mfma_f32_16x16x32_bf16 v[62:65], v[66:69], v[148:151], v[62:65]
	v_mfma_f32_16x16x32_bf16 v[54:57], v[82:85], v[148:151], v[54:57]
	v_mfma_f32_16x16x32_bf16 v[46:49], v[196:199], v[148:151], v[46:49]
	v_mfma_f32_16x16x32_bf16 v[38:41], v[204:207], v[148:151], v[38:41]
	v_mfma_f32_16x16x32_bf16 v[62:65], v[74:77], v[152:155], v[62:65]
	v_mfma_f32_16x16x32_bf16 v[58:61], v[66:69], v[156:159], v[58:61]
	v_mfma_f32_16x16x32_bf16 v[54:57], v[90:93], v[152:155], v[54:57]
	v_mfma_f32_16x16x32_bf16 v[50:53], v[82:85], v[156:159], v[50:53]
	v_mfma_f32_16x16x32_bf16 v[46:49], v[200:203], v[152:155], v[46:49]
	v_mfma_f32_16x16x32_bf16 v[42:45], v[196:199], v[156:159], v[42:45]
	v_mfma_f32_16x16x32_bf16 v[38:41], v[208:211], v[152:155], v[38:41]
	v_mfma_f32_16x16x32_bf16 v[34:37], v[204:207], v[156:159], v[34:37]
	v_mfma_f32_16x16x32_bf16 v[224:227], v[74:77], v[160:163], v[58:61]
	v_mfma_f32_16x16x32_bf16 v[228:231], v[90:93], v[160:163], v[50:53]
	v_mfma_f32_16x16x32_bf16 v[232:235], v[200:203], v[160:163], v[42:45]
	v_mfma_f32_16x16x32_bf16 v[148:151], v[208:211], v[160:163], v[34:37]
	s_setprio 0
	s_setprio 1
	v_mfma_f32_16x16x32_bf16 v[30:33], v[66:69], v[98:101], v[30:33]
	v_mfma_f32_16x16x32_bf16 v[22:25], v[82:85], v[98:101], v[22:25]
	v_mfma_f32_16x16x32_bf16 v[14:17], v[196:199], v[98:101], v[14:17]
	v_mfma_f32_16x16x32_bf16 v[6:9], v[204:207], v[98:101], v[6:9]
	v_mfma_f32_16x16x32_bf16 v[30:33], v[74:77], v[106:109], v[30:33]
	v_mfma_f32_16x16x32_bf16 v[26:29], v[66:69], v[114:117], v[26:29]
	v_mfma_f32_16x16x32_bf16 v[22:25], v[90:93], v[106:109], v[22:25]
	v_mfma_f32_16x16x32_bf16 v[18:21], v[82:85], v[114:117], v[18:21]
	v_mfma_f32_16x16x32_bf16 v[14:17], v[200:203], v[106:109], v[14:17]
	v_mfma_f32_16x16x32_bf16 v[10:13], v[196:199], v[114:117], v[10:13]
	v_mfma_f32_16x16x32_bf16 v[6:9], v[208:211], v[106:109], v[6:9]
	v_mfma_f32_16x16x32_bf16 v[2:5], v[204:207], v[114:117], v[2:5]
	v_mfma_f32_16x16x32_bf16 v[152:155], v[74:77], v[122:125], v[26:29]
	v_mfma_f32_16x16x32_bf16 v[156:159], v[90:93], v[122:125], v[18:21]
	v_mfma_f32_16x16x32_bf16 v[160:163], v[200:203], v[122:125], v[10:13]
	v_mfma_f32_16x16x32_bf16 v[196:199], v[208:211], v[122:125], v[2:5]
	s_setprio 0
	s_barrier
	s_nop 1
	ds_read_b128 v[2:5], v145
	ds_read_b128 v[10:13], v145 offset:1024
	ds_read_b128 v[200:203], v145 offset:2048
	ds_read_b128 v[204:207], v145 offset:3072
	ds_read_b128 v[18:21], v133 offset:32768
	ds_read_b128 v[26:29], v133 offset:33792
	ds_read_b128 v[34:37], v134 offset:32768
	ds_read_b128 v[42:45], v134 offset:33792
	ds_read_b128 v[50:53], v137 offset:32768
	ds_read_b128 v[58:61], v137 offset:33792
	ds_read_b128 v[208:211], v139 offset:32768
	ds_read_b128 v[236:239], v139 offset:33792
	s_waitcnt vmcnt(2)
	s_barrier
	s_waitcnt lgkmcnt(0)
	s_setprio 1
	s_waitcnt lgkmcnt(0)
	v_mfma_f32_16x16x32_bf16 v[66:69], v[18:21], v[2:5], v[126:129]
	v_mfma_f32_16x16x32_bf16 v[122:125], v[26:29], v[10:13], v[66:69]
	v_mfma_f32_16x16x32_bf16 v[66:69], v[18:21], v[200:203], v[140:143]
	v_mfma_f32_16x16x32_bf16 v[114:117], v[26:29], v[204:207], v[66:69]
	v_mfma_f32_16x16x32_bf16 v[66:69], v[34:37], v[2:5], v[118:121]
	v_mfma_f32_16x16x32_bf16 v[106:109], v[42:45], v[10:13], v[66:69]
	v_mfma_f32_16x16x32_bf16 v[66:69], v[34:37], v[200:203], v[212:215]
	v_mfma_f32_16x16x32_bf16 v[98:101], v[42:45], v[204:207], v[66:69]
	v_mfma_f32_16x16x32_bf16 v[66:69], v[50:53], v[2:5], v[110:113]
	v_mfma_f32_16x16x32_bf16 v[90:93], v[58:61], v[10:13], v[66:69]
	v_mfma_f32_16x16x32_bf16 v[66:69], v[50:53], v[200:203], v[216:219]
	v_mfma_f32_16x16x32_bf16 v[82:85], v[58:61], v[204:207], v[66:69]
	v_mfma_f32_16x16x32_bf16 v[66:69], v[208:211], v[2:5], v[102:105]
	v_mfma_f32_16x16x32_bf16 v[74:77], v[236:239], v[10:13], v[66:69]
	v_mfma_f32_16x16x32_bf16 v[66:69], v[208:211], v[200:203], v[220:223]
	v_mfma_f32_16x16x32_bf16 v[66:69], v[236:239], v[204:207], v[66:69]
	s_setprio 0
	s_barrier
; #define LDA(dst, b, h) for (int m = 0; m < 4; ++m) for (int k = 0; k < 2; ++k) \
;     dst[m][k] = *reinterpret_cast<const bf16x8*>((char*)SA(b, h) + lds_byte(wr * 64 + m * 16 + fr, k * 32 + fq * 8))
; #define LDB(dst, b, h) for (int n = 0; n < 2; ++n) for (int k = 0; k < 2; ++k) \
;     dst[n][k] = *reinterpret_cast<const bf16x8*>((char*)SB(b, h) + lds_byte(wc * 32 + n * 16 + fr, k * 32 + fq * 8))
; #define MMA(ai, bj, At, Bt_) do { __builtin_amdgcn_s_setprio(1); \
;     for (int m = 0; m < 4; ++m) for (int n = 0; n < 2; ++n) for (int k = 0; k < 2; ++k) \
;       acc[ai][bj][m][n] = __builtin_amdgcn_mfma_f32_16x16x32_bf16(At[m][k], Bt_[n][k], acc[ai][bj][m][n], 0, 0, 0); \
;     __builtin_amdgcn_s_setprio(0); } while (0)
; #define WAIT_V(n) asm volatile("s_waitcnt vmcnt(" #n ")" ::: "memory")
; #define WAIT_L(n) asm volatile("s_waitcnt lgkmcnt(" #n ")" ::: "memory")
; #define BAR __builtin_amdgcn_s_barrier()
;     ...
;       LDB(B1, 1, 1); WAIT_V(0); BAR; WAIT_L(0); MMA(0, 1, At, B1); BAR;
;       LDA(At, 1, 1); BAR; WAIT_L(0); MMA(1, 0, At, B0); MMA(1, 1, At, B1); BAR; }
;     if (wr == 0) BAR;
	ds_read_b128 v[140:143], v146
	ds_read_b128 v[212:215], v146 offset:1024
	ds_read_b128 v[216:219], v146 offset:2048
	ds_read_b128 v[144:147], v146 offset:3072
	s_waitcnt vmcnt(0)
	s_barrier
	s_waitcnt lgkmcnt(0)
	s_setprio 1
	s_waitcnt lgkmcnt(0)
	v_mfma_f32_16x16x32_bf16 v[94:97], v[18:21], v[140:143], v[94:97]
	v_mfma_f32_16x16x32_bf16 v[18:21], v[18:21], v[216:219], v[164:167]
	v_mfma_f32_16x16x32_bf16 v[118:121], v[26:29], v[144:147], v[18:21]
	v_mfma_f32_16x16x32_bf16 v[18:21], v[34:37], v[140:143], v[86:89]
	v_mfma_f32_16x16x32_bf16 v[110:113], v[42:45], v[212:215], v[18:21]
	v_mfma_f32_16x16x32_bf16 v[18:21], v[34:37], v[216:219], v[184:187]
	v_mfma_f32_16x16x32_bf16 v[102:105], v[42:45], v[144:147], v[18:21]
	v_mfma_f32_16x16x32_bf16 v[18:21], v[50:53], v[140:143], v[78:81]
	v_mfma_f32_16x16x32_bf16 v[126:129], v[26:29], v[212:215], v[94:97]
	v_mfma_f32_16x16x32_bf16 v[94:97], v[58:61], v[212:215], v[18:21]
	v_mfma_f32_16x16x32_bf16 v[18:21], v[50:53], v[216:219], v[188:191]
	v_mfma_f32_16x16x32_bf16 v[86:89], v[58:61], v[144:147], v[18:21]
	v_mfma_f32_16x16x32_bf16 v[18:21], v[208:211], v[140:143], v[70:73]
	v_mfma_f32_16x16x32_bf16 v[78:81], v[236:239], v[212:215], v[18:21]
	v_mfma_f32_16x16x32_bf16 v[18:21], v[208:211], v[216:219], v[192:195]
	v_mfma_f32_16x16x32_bf16 v[70:73], v[236:239], v[144:147], v[18:21]
	s_setprio 0
	s_barrier
	ds_read_b128 v[164:167], v133 offset:49152
	ds_read_b128 v[184:187], v133 offset:50176
	ds_read_b128 v[188:191], v134 offset:49152
	ds_read_b128 v[192:195], v134 offset:50176
	ds_read_b128 v[208:211], v137 offset:49152
	ds_read_b128 v[220:223], v137 offset:50176
	ds_read_b128 v[236:239], v139 offset:49152
	ds_read_b128 v[240:243], v139 offset:50176
	s_barrier
	s_waitcnt lgkmcnt(0)
	s_setprio 1
	s_waitcnt lgkmcnt(0)
	v_mfma_f32_16x16x32_bf16 v[18:21], v[164:167], v[2:5], v[62:65]
	v_mfma_f32_16x16x32_bf16 v[58:61], v[184:187], v[10:13], v[18:21]
	v_mfma_f32_16x16x32_bf16 v[18:21], v[164:167], v[200:203], v[224:227]
	v_mfma_f32_16x16x32_bf16 v[50:53], v[184:187], v[204:207], v[18:21]
	v_mfma_f32_16x16x32_bf16 v[18:21], v[188:191], v[2:5], v[54:57]
	v_mfma_f32_16x16x32_bf16 v[42:45], v[192:195], v[10:13], v[18:21]
	v_mfma_f32_16x16x32_bf16 v[18:21], v[188:191], v[200:203], v[228:231]
	v_mfma_f32_16x16x32_bf16 v[34:37], v[192:195], v[204:207], v[18:21]
	v_mfma_f32_16x16x32_bf16 v[18:21], v[208:211], v[2:5], v[46:49]
	v_mfma_f32_16x16x32_bf16 v[2:5], v[236:239], v[2:5], v[38:41]
	v_mfma_f32_16x16x32_bf16 v[26:29], v[220:223], v[10:13], v[18:21]
	v_mfma_f32_16x16x32_bf16 v[18:21], v[208:211], v[200:203], v[232:235]
	v_mfma_f32_16x16x32_bf16 v[10:13], v[240:243], v[10:13], v[2:5]
	v_mfma_f32_16x16x32_bf16 v[2:5], v[236:239], v[200:203], v[148:151]
	v_mfma_f32_16x16x32_bf16 v[18:21], v[220:223], v[204:207], v[18:21]
	v_mfma_f32_16x16x32_bf16 v[2:5], v[240:243], v[204:207], v[2:5]
	s_setprio 0
	s_setprio 1
	v_mfma_f32_16x16x32_bf16 v[30:33], v[164:167], v[140:143], v[30:33]
	v_mfma_f32_16x16x32_bf16 v[62:65], v[184:187], v[212:215], v[30:33]
	v_mfma_f32_16x16x32_bf16 v[30:33], v[164:167], v[216:219], v[152:155]
	v_mfma_f32_16x16x32_bf16 v[22:25], v[188:191], v[140:143], v[22:25]
	v_mfma_f32_16x16x32_bf16 v[14:17], v[208:211], v[140:143], v[14:17]
	v_mfma_f32_16x16x32_bf16 v[54:57], v[184:187], v[144:147], v[30:33]
	v_mfma_f32_16x16x32_bf16 v[46:49], v[192:195], v[212:215], v[22:25]
	v_mfma_f32_16x16x32_bf16 v[22:25], v[188:191], v[216:219], v[156:159]
	v_mfma_f32_16x16x32_bf16 v[30:33], v[220:223], v[212:215], v[14:17]
	v_mfma_f32_16x16x32_bf16 v[14:17], v[208:211], v[216:219], v[160:163]
	v_mfma_f32_16x16x32_bf16 v[6:9], v[236:239], v[140:143], v[6:9]
	v_mfma_f32_16x16x32_bf16 v[38:41], v[192:195], v[144:147], v[22:25]
	v_mfma_f32_16x16x32_bf16 v[22:25], v[220:223], v[144:147], v[14:17]
	v_mfma_f32_16x16x32_bf16 v[14:17], v[240:243], v[212:215], v[6:9]
	v_mfma_f32_16x16x32_bf16 v[6:9], v[236:239], v[216:219], v[196:199]
	v_mfma_f32_16x16x32_bf16 v[6:9], v[240:243], v[144:147], v[6:9]
	s_setprio 0
	v_readlane_b32 s4, v245, 33
	v_readlane_b32 s5, v245, 34
	s_and_b64 vcc, exec, s[4:5]
	s_barrier
	s_cbranch_vccz .LBB0_158
	s_barrier

; #define LDA(dst, b, h) for (int m = 0; m < 4; ++m) for (int k = 0; k < 2; ++k) \
;     dst[m][k] = *reinterpret_cast<const bf16x8*>((char*)SA(b, h) + lds_byte(wr * 64 + m * 16 + fr, k * 32 + fq * 8))
; #define LDB(dst, b, h) for (int n = 0; n < 2; ++n) for (int k = 0; k < 2; ++k) \
;     dst[n][k] = *reinterpret_cast<const bf16x8*>((char*)SB(b, h) + lds_byte(wc * 32 + n * 16 + fr, k * 32 + fq * 8))
; #define MMA(ai, bj, At, Bt_) do { __builtin_amdgcn_s_setprio(1); \
;     for (int m = 0; m < 4; ++m) for (int n = 0; n < 2; ++n) for (int k = 0; k < 2; ++k) \
;       acc[ai][bj][m][n] = __builtin_amdgcn_mfma_f32_16x16x32_bf16(At[m][k], Bt_[n][k], acc[ai][bj][m][n], 0, 0, 0); \
;     __builtin_amdgcn_s_setprio(0); } while (0)
; #define WAIT_L(n) asm volatile("s_waitcnt lgkmcnt(" #n ")" ::: "memory")
; #define BAR __builtin_amdgcn_s_barrier()
; #define SCHED __builtin_amdgcn_sched_barrier(0)
;     ...
;       LDB(B0, 0, 0); SCHED; LDA(At, 0, 0); STAGE(SA(1, 1), A, brow + HALF, t + 1);
;       WAIT_L(8); BAR; WAIT_L(0); MMA(0, 0, At, B0); BAR; SCHED;
;       LDB(B1, 0, 1); STAGE(SB(0, 0), Bt, bcol, t + 2);
;       BAR; WAIT_L(0); MMA(0, 1, At, B1); BAR;
;       LDA(At, 0, 1); STAGE(SA(0, 0), A, brow, t + 2);
;       BAR; WAIT_L(0); MMA(1, 0, At, B0); BAR; SCHED;
.LBB0_202:
	v_add_u32_e32 v143, s2, v142
	ds_read_b128 v[146:149], v143
	ds_read_b128 v[150:153], v143 offset:1024
	ds_read_b128 v[154:157], v143 offset:2048
	ds_read_b128 v[158:161], v143 offset:3072
	s_add_u32 s66, s50, s16
	s_addc_u32 s67, s51, s17
	s_add_i32 s58, s21, 0xc000
	ds_read_b128 v[162:165], v133
	ds_read_b128 v[184:187], v133 offset:1024
	ds_read_b128 v[188:191], v134
	ds_read_b128 v[192:195], v134 offset:1024
	ds_read_b128 v[196:199], v137
	ds_read_b128 v[200:203], v137 offset:1024
	ds_read_b128 v[204:207], v139
	ds_read_b128 v[208:211], v139 offset:1024
	s_mov_b32 m0, s58
	v_lshl_add_u64 v[144:145], s[66:67], 0, v[0:1]
	s_add_i32 s57, s21, 0xe000
	global_load_lds_dwordx4 v[144:145], off
	v_lshl_add_u64 v[144:145], s[66:67], 0, v[140:141]
	s_mov_b32 m0, s57
	s_nop 0
	global_load_lds_dwordx4 v[144:145], off
	s_barrier
	s_waitcnt lgkmcnt(0)
	s_waitcnt lgkmcnt(0)
	v_mfma_f32_16x16x32_bf16 v[126:129], v[162:165], v[146:149], v[126:129]
	v_mfma_f32_16x16x32_bf16 v[122:125], v[162:165], v[154:157], v[122:125]
	v_mfma_f32_16x16x32_bf16 v[118:121], v[188:191], v[146:149], v[118:121]
	v_mfma_f32_16x16x32_bf16 v[114:117], v[188:191], v[154:157], v[114:117]
	v_mfma_f32_16x16x32_bf16 v[110:113], v[196:199], v[146:149], v[110:113]
	v_mfma_f32_16x16x32_bf16 v[106:109], v[196:199], v[154:157], v[106:109]
	v_mfma_f32_16x16x32_bf16 v[102:105], v[204:207], v[146:149], v[102:105]
	v_mfma_f32_16x16x32_bf16 v[98:101], v[204:207], v[154:157], v[98:101]
	v_mfma_f32_16x16x32_bf16 v[126:129], v[184:187], v[150:153], v[126:129]
	v_mfma_f32_16x16x32_bf16 v[122:125], v[184:187], v[158:161], v[122:125]
	v_mfma_f32_16x16x32_bf16 v[118:121], v[192:195], v[150:153], v[118:121]
	v_mfma_f32_16x16x32_bf16 v[114:117], v[192:195], v[158:161], v[114:117]
	v_mfma_f32_16x16x32_bf16 v[110:113], v[200:203], v[150:153], v[110:113]
	v_mfma_f32_16x16x32_bf16 v[106:109], v[200:203], v[158:161], v[106:109]
	v_mfma_f32_16x16x32_bf16 v[102:105], v[208:211], v[150:153], v[102:105]
	v_mfma_f32_16x16x32_bf16 v[98:101], v[208:211], v[158:161], v[98:101]
	s_barrier
	s_add_i32 s55, s55, 2
	s_add_u32 s59, s11, s16
	s_addc_u32 s63, s44, s17
	s_add_u32 s66, s59, 0x100
	v_add_u32_e32 v144, s76, v142
	s_addc_u32 s67, s63, 0
	s_mov_b32 m0, s29
	ds_read_b128 v[212:215], v144
	ds_read_b128 v[216:219], v144 offset:1024
	ds_read_b128 v[220:223], v144 offset:2048
	ds_read_b128 v[224:227], v144 offset:3072
	s_nop 0
	v_lshl_add_u64 v[166:167], s[66:67], 0, v[0:1]
	global_load_lds_dwordx4 v[166:167], off
	v_lshl_add_u64 v[166:167], s[66:67], 0, v[140:141]
	s_mov_b32 m0, s30
	s_nop 0
	global_load_lds_dwordx4 v[166:167], off
	s_barrier
	s_waitcnt lgkmcnt(0)
	s_waitcnt lgkmcnt(0)
	v_mfma_f32_16x16x32_bf16 v[94:97], v[162:165], v[212:215], v[94:97]
	v_mfma_f32_16x16x32_bf16 v[90:93], v[162:165], v[220:223], v[90:93]
	v_mfma_f32_16x16x32_bf16 v[86:89], v[188:191], v[212:215], v[86:89]
	v_mfma_f32_16x16x32_bf16 v[82:85], v[188:191], v[220:223], v[82:85]
	v_mfma_f32_16x16x32_bf16 v[78:81], v[196:199], v[212:215], v[78:81]
	v_mfma_f32_16x16x32_bf16 v[74:77], v[196:199], v[220:223], v[74:77]
	v_mfma_f32_16x16x32_bf16 v[70:73], v[204:207], v[212:215], v[70:73]
	v_mfma_f32_16x16x32_bf16 v[66:69], v[204:207], v[220:223], v[66:69]
	v_mfma_f32_16x16x32_bf16 v[94:97], v[184:187], v[216:219], v[94:97]
	v_mfma_f32_16x16x32_bf16 v[90:93], v[184:187], v[224:227], v[90:93]
	v_mfma_f32_16x16x32_bf16 v[86:89], v[192:195], v[216:219], v[86:89]
	v_mfma_f32_16x16x32_bf16 v[82:85], v[192:195], v[224:227], v[82:85]
	v_mfma_f32_16x16x32_bf16 v[78:81], v[200:203], v[216:219], v[78:81]
	v_mfma_f32_16x16x32_bf16 v[74:77], v[200:203], v[224:227], v[74:77]
	v_mfma_f32_16x16x32_bf16 v[70:73], v[208:211], v[216:219], v[70:73]
	v_mfma_f32_16x16x32_bf16 v[66:69], v[208:211], v[224:227], v[66:69]
	s_add_u32 s65, s13, s16
	s_addc_u32 s70, s45, s17
	s_add_u32 s66, s65, 0x100
	s_addc_u32 s67, s70, 0
	s_mov_b32 m0, s21
	s_barrier
	ds_read_b128 v[162:165], v133 offset:16384
	ds_read_b128 v[184:187], v133 offset:17408
	ds_read_b128 v[188:191], v134 offset:16384
	ds_read_b128 v[192:195], v134 offset:17408
	ds_read_b128 v[196:199], v137 offset:16384
	ds_read_b128 v[200:203], v137 offset:17408
	ds_read_b128 v[204:207], v139 offset:16384
	ds_read_b128 v[208:211], v139 offset:17408
	s_nop 0
	v_lshl_add_u64 v[166:167], s[66:67], 0, v[0:1]
	global_load_lds_dwordx4 v[166:167], off
	v_lshl_add_u64 v[166:167], s[66:67], 0, v[140:141]
	s_mov_b32 m0, s31
	s_nop 0
	global_load_lds_dwordx4 v[166:167], off
	s_barrier
	s_waitcnt lgkmcnt(0)
	s_waitcnt lgkmcnt(0)
	v_mfma_f32_16x16x32_bf16 v[62:65], v[162:165], v[146:149], v[62:65]
	v_mfma_f32_16x16x32_bf16 v[58:61], v[162:165], v[154:157], v[58:61]
	v_mfma_f32_16x16x32_bf16 v[54:57], v[188:191], v[146:149], v[54:57]
	v_mfma_f32_16x16x32_bf16 v[50:53], v[188:191], v[154:157], v[50:53]
	v_mfma_f32_16x16x32_bf16 v[46:49], v[196:199], v[146:149], v[46:49]
	v_mfma_f32_16x16x32_bf16 v[42:45], v[196:199], v[154:157], v[42:45]
	v_mfma_f32_16x16x32_bf16 v[38:41], v[204:207], v[146:149], v[38:41]
	v_mfma_f32_16x16x32_bf16 v[34:37], v[204:207], v[154:157], v[34:37]
	v_mfma_f32_16x16x32_bf16 v[62:65], v[184:187], v[150:153], v[62:65]
	v_mfma_f32_16x16x32_bf16 v[58:61], v[184:187], v[158:161], v[58:61]
	v_mfma_f32_16x16x32_bf16 v[54:57], v[192:195], v[150:153], v[54:57]
	v_mfma_f32_16x16x32_bf16 v[50:53], v[192:195], v[158:161], v[50:53]
	v_mfma_f32_16x16x32_bf16 v[46:49], v[200:203], v[150:153], v[46:49]
	v_mfma_f32_16x16x32_bf16 v[42:45], v[200:203], v[158:161], v[42:45]
	v_mfma_f32_16x16x32_bf16 v[38:41], v[208:211], v[150:153], v[38:41]
	v_mfma_f32_16x16x32_bf16 v[34:37], v[208:211], v[158:161], v[34:37]
	s_barrier
; #define LDA(dst, b, h) for (int m = 0; m < 4; ++m) for (int k = 0; k < 2; ++k) \
;     dst[m][k] = *reinterpret_cast<const bf16x8*>((char*)SA(b, h) + lds_byte(wr * 64 + m * 16 + fr, k * 32 + fq * 8))
; #define LDB(dst, b, h) for (int n = 0; n < 2; ++n) for (int k = 0; k < 2; ++k) \
;     dst[n][k] = *reinterpret_cast<const bf16x8*>((char*)SB(b, h) + lds_byte(wc * 32 + n * 16 + fr, k * 32 + fq * 8))
; #define MMA(ai, bj, At, Bt_) do { __builtin_amdgcn_s_setprio(1); \
;     for (int m = 0; m < 4; ++m) for (int n = 0; n < 2; ++n) for (int k = 0; k < 2; ++k) \
;       acc[ai][bj][m][n] = __builtin_amdgcn_mfma_f32_16x16x32_bf16(At[m][k], Bt_[n][k], acc[ai][bj][m][n], 0, 0, 0); \
;     __builtin_amdgcn_s_setprio(0); } while (0)
; #define WAIT_V(n) asm volatile("s_waitcnt vmcnt(" #n ")" ::: "memory")
; #define WAIT_L(n) asm volatile("s_waitcnt lgkmcnt(" #n ")" ::: "memory")
; #define BAR __builtin_amdgcn_s_barrier()
; #define SCHED __builtin_amdgcn_sched_barrier(0)
;     ...
;       STAGE(SB(0, 1), Bt, bcol + HALF, t + 2);
;       WAIT_V(6); BAR; MMA(1, 1, At, B1); BAR;
;       LDB(B0, 1, 0); SCHED; LDA(At, 1, 0); STAGE(SA(0, 1), A, brow + HALF, t + 2);
;       WAIT_L(8); BAR; WAIT_L(0); MMA(0, 0, At, B0); BAR; SCHED;
;       LDB(B1, 1, 1); STAGE(SB(1, 0), Bt, bcol, t + 3);
;       BAR; WAIT_L(0); MMA(0, 1, At, B1); BAR;
;       LDA(At, 1, 1); STAGE(SA(1, 0), A, brow, t + 3);
	s_add_u32 s66, s59, 0x80100
	s_addc_u32 s67, s63, 0
	s_mov_b32 m0, s34
	s_nop 0
	v_lshl_add_u64 v[146:147], s[66:67], 0, v[0:1]
	global_load_lds_dwordx4 v[146:147], off
	v_lshl_add_u64 v[146:147], s[66:67], 0, v[140:141]
	s_mov_b32 m0, s35
	s_nop 0
	global_load_lds_dwordx4 v[146:147], off
	s_waitcnt vmcnt(6)
	s_barrier
	v_mfma_f32_16x16x32_bf16 v[30:33], v[162:165], v[212:215], v[30:33]
	v_mfma_f32_16x16x32_bf16 v[26:29], v[162:165], v[220:223], v[26:29]
	v_mfma_f32_16x16x32_bf16 v[22:25], v[188:191], v[212:215], v[22:25]
	v_mfma_f32_16x16x32_bf16 v[18:21], v[188:191], v[220:223], v[18:21]
	v_mfma_f32_16x16x32_bf16 v[14:17], v[196:199], v[212:215], v[14:17]
	v_mfma_f32_16x16x32_bf16 v[10:13], v[196:199], v[220:223], v[10:13]
	v_mfma_f32_16x16x32_bf16 v[6:9], v[204:207], v[212:215], v[6:9]
	v_mfma_f32_16x16x32_bf16 v[2:5], v[204:207], v[220:223], v[2:5]
	v_mfma_f32_16x16x32_bf16 v[30:33], v[184:187], v[216:219], v[30:33]
	v_mfma_f32_16x16x32_bf16 v[26:29], v[184:187], v[224:227], v[26:29]
	v_mfma_f32_16x16x32_bf16 v[22:25], v[192:195], v[216:219], v[22:25]
	v_mfma_f32_16x16x32_bf16 v[18:21], v[192:195], v[224:227], v[18:21]
	v_mfma_f32_16x16x32_bf16 v[14:17], v[200:203], v[216:219], v[14:17]
	v_mfma_f32_16x16x32_bf16 v[10:13], v[200:203], v[224:227], v[10:13]
	v_mfma_f32_16x16x32_bf16 v[6:9], v[208:211], v[216:219], v[6:9]
	v_mfma_f32_16x16x32_bf16 v[2:5], v[208:211], v[224:227], v[2:5]
	v_add_u32_e32 v145, s77, v142
	s_barrier
	ds_read_b128 v[148:151], v145
	ds_read_b128 v[152:155], v145 offset:1024
	ds_read_b128 v[156:159], v145 offset:2048
	ds_read_b128 v[160:163], v145 offset:3072
	s_add_u32 s66, s65, 0x80100
	s_addc_u32 s67, s70, 0
	s_mov_b32 m0, s37
	ds_read_b128 v[164:167], v133 offset:32768
	ds_read_b128 v[184:187], v133 offset:33792
	ds_read_b128 v[188:191], v134 offset:32768
	ds_read_b128 v[192:195], v134 offset:33792
	ds_read_b128 v[196:199], v137 offset:32768
	ds_read_b128 v[200:203], v137 offset:33792
	ds_read_b128 v[204:207], v139 offset:32768
	ds_read_b128 v[208:211], v139 offset:33792
	s_nop 0
	v_lshl_add_u64 v[146:147], s[66:67], 0, v[0:1]
	global_load_lds_dwordx4 v[146:147], off
	v_lshl_add_u64 v[146:147], s[66:67], 0, v[140:141]
	s_mov_b32 m0, s38
	s_nop 0
	global_load_lds_dwordx4 v[146:147], off
	s_barrier
	s_waitcnt lgkmcnt(0)
	s_waitcnt lgkmcnt(0)
	v_mfma_f32_16x16x32_bf16 v[126:129], v[164:167], v[148:151], v[126:129]
	v_mfma_f32_16x16x32_bf16 v[122:125], v[164:167], v[156:159], v[122:125]
	v_mfma_f32_16x16x32_bf16 v[118:121], v[188:191], v[148:151], v[118:121]
	v_mfma_f32_16x16x32_bf16 v[114:117], v[188:191], v[156:159], v[114:117]
	v_mfma_f32_16x16x32_bf16 v[110:113], v[196:199], v[148:151], v[110:113]
	v_mfma_f32_16x16x32_bf16 v[106:109], v[196:199], v[156:159], v[106:109]
	v_mfma_f32_16x16x32_bf16 v[102:105], v[204:207], v[148:151], v[102:105]
	v_mfma_f32_16x16x32_bf16 v[98:101], v[204:207], v[156:159], v[98:101]
	v_mfma_f32_16x16x32_bf16 v[126:129], v[184:187], v[152:155], v[126:129]
	v_mfma_f32_16x16x32_bf16 v[122:125], v[184:187], v[160:163], v[122:125]
	v_mfma_f32_16x16x32_bf16 v[118:121], v[192:195], v[152:155], v[118:121]
	v_mfma_f32_16x16x32_bf16 v[114:117], v[192:195], v[160:163], v[114:117]
	v_mfma_f32_16x16x32_bf16 v[110:113], v[200:203], v[152:155], v[110:113]
	v_mfma_f32_16x16x32_bf16 v[106:109], v[200:203], v[160:163], v[106:109]
	v_mfma_f32_16x16x32_bf16 v[102:105], v[208:211], v[152:155], v[102:105]
	v_mfma_f32_16x16x32_bf16 v[98:101], v[208:211], v[160:163], v[98:101]
	s_barrier
	s_add_u32 s66, s59, 0x180
	v_add_u32_e32 v146, s78, v142
	s_addc_u32 s67, s63, 0
	s_mov_b32 m0, s39
	ds_read_b128 v[212:215], v146
	ds_read_b128 v[216:219], v146 offset:1024
	ds_read_b128 v[220:223], v146 offset:2048
	ds_read_b128 v[224:227], v146 offset:3072
	s_nop 0
	v_lshl_add_u64 v[228:229], s[66:67], 0, v[0:1]
	global_load_lds_dwordx4 v[228:229], off
	v_lshl_add_u64 v[228:229], s[66:67], 0, v[140:141]
	s_mov_b32 m0, s40
	s_nop 0
	global_load_lds_dwordx4 v[228:229], off
	s_barrier
	s_waitcnt lgkmcnt(0)
	s_waitcnt lgkmcnt(0)
	v_mfma_f32_16x16x32_bf16 v[94:97], v[164:167], v[212:215], v[94:97]
	v_mfma_f32_16x16x32_bf16 v[90:93], v[164:167], v[220:223], v[90:93]
	v_mfma_f32_16x16x32_bf16 v[86:89], v[188:191], v[212:215], v[86:89]
	v_mfma_f32_16x16x32_bf16 v[82:85], v[188:191], v[220:223], v[82:85]
	v_mfma_f32_16x16x32_bf16 v[78:81], v[196:199], v[212:215], v[78:81]
	v_mfma_f32_16x16x32_bf16 v[74:77], v[196:199], v[220:223], v[74:77]
	v_mfma_f32_16x16x32_bf16 v[70:73], v[204:207], v[212:215], v[70:73]
	v_mfma_f32_16x16x32_bf16 v[66:69], v[204:207], v[220:223], v[66:69]
	v_mfma_f32_16x16x32_bf16 v[94:97], v[184:187], v[216:219], v[94:97]
	v_mfma_f32_16x16x32_bf16 v[90:93], v[184:187], v[224:227], v[90:93]
	v_mfma_f32_16x16x32_bf16 v[86:89], v[192:195], v[216:219], v[86:89]
	v_mfma_f32_16x16x32_bf16 v[82:85], v[192:195], v[224:227], v[82:85]
	v_mfma_f32_16x16x32_bf16 v[78:81], v[200:203], v[216:219], v[78:81]
	v_mfma_f32_16x16x32_bf16 v[74:77], v[200:203], v[224:227], v[74:77]
	v_mfma_f32_16x16x32_bf16 v[70:73], v[208:211], v[216:219], v[70:73]
	v_mfma_f32_16x16x32_bf16 v[66:69], v[208:211], v[224:227], v[66:69]
	s_add_u32 s66, s65, 0x180
	s_addc_u32 s67, s70, 0
	s_mov_b32 m0, s41
	s_barrier
	ds_read_b128 v[164:167], v133 offset:49152
	ds_read_b128 v[184:187], v133 offset:50176
	ds_read_b128 v[188:191], v134 offset:49152
	ds_read_b128 v[192:195], v134 offset:50176
	ds_read_b128 v[196:199], v137 offset:49152
	ds_read_b128 v[200:203], v137 offset:50176
	ds_read_b128 v[204:207], v139 offset:49152
	ds_read_b128 v[208:211], v139 offset:50176
	s_nop 0
	v_lshl_add_u64 v[228:229], s[66:67], 0, v[0:1]
	global_load_lds_dwordx4 v[228:229], off
	v_lshl_add_u64 v[228:229], s[66:67], 0, v[140:141]
	s_mov_b32 m0, s42
	s_nop 0
	global_load_lds_dwordx4 v[228:229], off
	s_barrier
; #define LDA(dst, b, h) for (int m = 0; m < 4; ++m) for (int k = 0; k < 2; ++k) \
;     dst[m][k] = *reinterpret_cast<const bf16x8*>((char*)SA(b, h) + lds_byte(wr * 64 + m * 16 + fr, k * 32 + fq * 8))
; #define LDB(dst, b, h) for (int n = 0; n < 2; ++n) for (int k = 0; k < 2; ++k) \
;     dst[n][k] = *reinterpret_cast<const bf16x8*>((char*)SB(b, h) + lds_byte(wc * 32 + n * 16 + fr, k * 32 + fq * 8))
; #define MMA(ai, bj, At, Bt_) do { __builtin_amdgcn_s_setprio(1); \
;     for (int m = 0; m < 4; ++m) for (int n = 0; n < 2; ++n) for (int k = 0; k < 2; ++k) \
;       acc[ai][bj][m][n] = __builtin_amdgcn_mfma_f32_16x16x32_bf16(At[m][k], Bt_[n][k], acc[ai][bj][m][n], 0, 0, 0); \
;     __builtin_amdgcn_s_setprio(0); } while (0)
; #define WAIT_V(n) asm volatile("s_waitcnt vmcnt(" #n ")" ::: "memory")
; #define WAIT_L(n) asm volatile("s_waitcnt lgkmcnt(" #n ")" ::: "memory")
; #define BAR __builtin_amdgcn_s_barrier()
; #define SCHED __builtin_amdgcn_sched_barrier(0)
;     ...
;       BAR; WAIT_L(0); MMA(1, 0, At, B0); BAR; SCHED;
;       STAGE(SB(1, 1), Bt, bcol + HALF, t + 3);
;       WAIT_V(6); BAR; MMA(1, 1, At, B1); BAR;
;     }
;     { LDB(B0, 0, 0); LDA(At, 0, 0); STAGE(SA(1, 1), A, brow + HALF, nt - 1);
;       BAR; WAIT_L(0); MMA(0, 0, At, B0); BAR;
;       LDB(B1, 0, 1); BAR; WAIT_L(0); MMA(0, 1, At, B1); BAR;
	s_waitcnt lgkmcnt(0)
	s_waitcnt lgkmcnt(0)
	v_mfma_f32_16x16x32_bf16 v[62:65], v[164:167], v[148:151], v[62:65]
	v_mfma_f32_16x16x32_bf16 v[58:61], v[164:167], v[156:159], v[58:61]
	v_mfma_f32_16x16x32_bf16 v[54:57], v[188:191], v[148:151], v[54:57]
	v_mfma_f32_16x16x32_bf16 v[50:53], v[188:191], v[156:159], v[50:53]
	v_mfma_f32_16x16x32_bf16 v[46:49], v[196:199], v[148:151], v[46:49]
	v_mfma_f32_16x16x32_bf16 v[42:45], v[196:199], v[156:159], v[42:45]
	v_mfma_f32_16x16x32_bf16 v[38:41], v[204:207], v[148:151], v[38:41]
	v_mfma_f32_16x16x32_bf16 v[34:37], v[204:207], v[156:159], v[34:37]
	v_mfma_f32_16x16x32_bf16 v[62:65], v[184:187], v[152:155], v[62:65]
	v_mfma_f32_16x16x32_bf16 v[58:61], v[184:187], v[160:163], v[58:61]
	v_mfma_f32_16x16x32_bf16 v[54:57], v[192:195], v[152:155], v[54:57]
	v_mfma_f32_16x16x32_bf16 v[50:53], v[192:195], v[160:163], v[50:53]
	v_mfma_f32_16x16x32_bf16 v[46:49], v[200:203], v[152:155], v[46:49]
	v_mfma_f32_16x16x32_bf16 v[42:45], v[200:203], v[160:163], v[42:45]
	v_mfma_f32_16x16x32_bf16 v[38:41], v[208:211], v[152:155], v[38:41]
	v_mfma_f32_16x16x32_bf16 v[34:37], v[208:211], v[160:163], v[34:37]
	s_barrier
	s_add_u32 s66, s59, 0x80180
	s_addc_u32 s67, s63, 0
	s_mov_b32 m0, s18
	s_nop 0
	v_lshl_add_u64 v[148:149], s[66:67], 0, v[0:1]
	global_load_lds_dwordx4 v[148:149], off
	v_lshl_add_u64 v[148:149], s[66:67], 0, v[140:141]
	s_mov_b32 m0, s19
	s_nop 0
	global_load_lds_dwordx4 v[148:149], off
	s_waitcnt vmcnt(6)
	s_barrier
	v_mfma_f32_16x16x32_bf16 v[30:33], v[164:167], v[212:215], v[30:33]
	v_mfma_f32_16x16x32_bf16 v[26:29], v[164:167], v[220:223], v[26:29]
	v_mfma_f32_16x16x32_bf16 v[22:25], v[188:191], v[212:215], v[22:25]
	v_mfma_f32_16x16x32_bf16 v[18:21], v[188:191], v[220:223], v[18:21]
	v_mfma_f32_16x16x32_bf16 v[14:17], v[196:199], v[212:215], v[14:17]
	v_mfma_f32_16x16x32_bf16 v[10:13], v[196:199], v[220:223], v[10:13]
	v_mfma_f32_16x16x32_bf16 v[6:9], v[204:207], v[212:215], v[6:9]
	v_mfma_f32_16x16x32_bf16 v[2:5], v[204:207], v[220:223], v[2:5]
	v_mfma_f32_16x16x32_bf16 v[30:33], v[184:187], v[216:219], v[30:33]
	v_mfma_f32_16x16x32_bf16 v[26:29], v[184:187], v[224:227], v[26:29]
	v_mfma_f32_16x16x32_bf16 v[22:25], v[192:195], v[216:219], v[22:25]
	v_mfma_f32_16x16x32_bf16 v[18:21], v[192:195], v[224:227], v[18:21]
	v_mfma_f32_16x16x32_bf16 v[14:17], v[200:203], v[216:219], v[14:17]
	v_mfma_f32_16x16x32_bf16 v[10:13], v[200:203], v[224:227], v[10:13]
	v_mfma_f32_16x16x32_bf16 v[6:9], v[208:211], v[216:219], v[6:9]
	v_mfma_f32_16x16x32_bf16 v[2:5], v[208:211], v[224:227], v[2:5]
	s_add_u32 s11, s11, 0x100
	s_addc_u32 s44, s44, 0
	s_add_u32 s13, s13, 0x100
	s_addc_u32 s45, s45, 0
	s_add_u32 s50, s50, 0x100
	s_addc_u32 s51, s51, 0
	s_cmp_ge_u32 s55, s43
	s_barrier
	s_cbranch_scc0 .LBB0_202
	s_add_i32 s11, s48, s20
	s_add_i32 s48, s11, -1
	s_lshl_b64 s[16:17], s[48:49], 7
	s_add_u32 s11, s74, s16
	s_addc_u32 s13, s75, s17
	s_add_u32 s4, s11, s4
	s_addc_u32 s5, s13, s5
	s_mov_b32 m0, s58
	ds_read_b128 v[148:151], v143
	ds_read_b128 v[152:155], v143 offset:1024
	ds_read_b128 v[156:159], v143 offset:2048
	ds_read_b128 v[160:163], v143 offset:3072
	ds_read_b128 v[164:167], v133
	ds_read_b128 v[184:187], v133 offset:1024
	ds_read_b128 v[188:191], v134
	ds_read_b128 v[192:195], v134 offset:1024
	ds_read_b128 v[196:199], v137
	ds_read_b128 v[200:203], v137 offset:1024
	ds_read_b128 v[204:207], v139
	ds_read_b128 v[208:211], v139 offset:1024
	s_nop 0
	v_lshl_add_u64 v[142:143], s[4:5], 0, v[0:1]
	global_load_lds_dwordx4 v[142:143], off
	v_lshl_add_u64 v[140:141], s[4:5], 0, v[140:141]
	s_mov_b32 m0, s57
	s_nop 0
	global_load_lds_dwordx4 v[140:141], off
	s_barrier
	s_waitcnt lgkmcnt(0)
	s_setprio 1
	s_waitcnt lgkmcnt(0)
	v_mfma_f32_16x16x32_bf16 v[126:129], v[164:167], v[148:151], v[126:129]
	v_mfma_f32_16x16x32_bf16 v[122:125], v[164:167], v[156:159], v[122:125]
	v_mfma_f32_16x16x32_bf16 v[118:121], v[188:191], v[148:151], v[118:121]
	v_mfma_f32_16x16x32_bf16 v[110:113], v[196:199], v[148:151], v[110:113]
	v_mfma_f32_16x16x32_bf16 v[106:109], v[196:199], v[156:159], v[106:109]
	v_mfma_f32_16x16x32_bf16 v[102:105], v[204:207], v[148:151], v[102:105]
	v_mfma_f32_16x16x32_bf16 v[98:101], v[204:207], v[156:159], v[98:101]
	v_mfma_f32_16x16x32_bf16 v[126:129], v[184:187], v[152:155], v[126:129]
	v_mfma_f32_16x16x32_bf16 v[122:125], v[184:187], v[160:163], v[122:125]
	v_mfma_f32_16x16x32_bf16 v[118:121], v[192:195], v[152:155], v[118:121]
	v_mfma_f32_16x16x32_bf16 v[114:117], v[188:191], v[156:159], v[114:117]
	v_mfma_f32_16x16x32_bf16 v[110:113], v[200:203], v[152:155], v[110:113]
	v_mfma_f32_16x16x32_bf16 v[106:109], v[200:203], v[160:163], v[106:109]
	v_mfma_f32_16x16x32_bf16 v[102:105], v[208:211], v[152:155], v[102:105]
	v_mfma_f32_16x16x32_bf16 v[98:101], v[208:211], v[160:163], v[98:101]
	v_mfma_f32_16x16x32_bf16 v[140:143], v[192:195], v[160:163], v[114:117]
	s_setprio 0
	s_barrier
	s_nop 0
	ds_read_b128 v[114:117], v144
	ds_read_b128 v[212:215], v144 offset:1024
	ds_read_b128 v[216:219], v144 offset:2048
	ds_read_b128 v[220:223], v144 offset:3072
	s_barrier
; #define LDA(dst, b, h) for (int m = 0; m < 4; ++m) for (int k = 0; k < 2; ++k) \
;     dst[m][k] = *reinterpret_cast<const bf16x8*>((char*)SA(b, h) + lds_byte(wr * 64 + m * 16 + fr, k * 32 + fq * 8))
; #define LDB(dst, b, h) for (int n = 0; n < 2; ++n) for (int k = 0; k < 2; ++k) \
;     dst[n][k] = *reinterpret_cast<const bf16x8*>((char*)SB(b, h) + lds_byte(wc * 32 + n * 16 + fr, k * 32 + fq * 8))
; #define MMA(ai, bj, At, Bt_) do { __builtin_amdgcn_s_setprio(1); \
;     for (int m = 0; m < 4; ++m) for (int n = 0; n < 2; ++n) for (int k = 0; k < 2; ++k) \
;       acc[ai][bj][m][n] = __builtin_amdgcn_mfma_f32_16x16x32_bf16(At[m][k], Bt_[n][k], acc[ai][bj][m][n], 0, 0, 0); \
;     __builtin_amdgcn_s_setprio(0); } while (0)
; #define WAIT_V(n) asm volatile("s_waitcnt vmcnt(" #n ")" ::: "memory")
; #define WAIT_L(n) asm volatile("s_waitcnt lgkmcnt(" #n ")" ::: "memory")
; #define BAR __builtin_amdgcn_s_barrier()
;     ...
;       LDB(B1, 0, 1); BAR; WAIT_L(0); MMA(0, 1, At, B1); BAR;
;       LDA(At, 0, 1); WAIT_V(4); BAR; WAIT_L(0); MMA(1, 0, At, B0); MMA(1, 1, At, B1); BAR; }
;     { LDB(B0, 1, 0); LDA(At, 1, 0); WAIT_V(2); BAR; WAIT_L(0); MMA(0, 0, At, B0); BAR;
	s_waitcnt lgkmcnt(0)
	s_setprio 1
	s_waitcnt lgkmcnt(0)
	v_mfma_f32_16x16x32_bf16 v[90:93], v[164:167], v[216:219], v[90:93]
	v_mfma_f32_16x16x32_bf16 v[86:89], v[188:191], v[114:117], v[86:89]
	v_mfma_f32_16x16x32_bf16 v[94:97], v[164:167], v[114:117], v[94:97]
	v_mfma_f32_16x16x32_bf16 v[90:93], v[184:187], v[220:223], v[90:93]
	v_mfma_f32_16x16x32_bf16 v[86:89], v[192:195], v[212:215], v[86:89]
	v_mfma_f32_16x16x32_bf16 v[82:85], v[188:191], v[216:219], v[82:85]
	v_mfma_f32_16x16x32_bf16 v[78:81], v[196:199], v[114:117], v[78:81]
	v_mfma_f32_16x16x32_bf16 v[74:77], v[196:199], v[216:219], v[74:77]
	v_mfma_f32_16x16x32_bf16 v[70:73], v[204:207], v[114:117], v[70:73]
	v_mfma_f32_16x16x32_bf16 v[66:69], v[204:207], v[216:219], v[66:69]
	v_mfma_f32_16x16x32_bf16 v[224:227], v[184:187], v[212:215], v[94:97]
	v_mfma_f32_16x16x32_bf16 v[164:167], v[192:195], v[220:223], v[82:85]
	v_mfma_f32_16x16x32_bf16 v[184:187], v[200:203], v[212:215], v[78:81]
	v_mfma_f32_16x16x32_bf16 v[188:191], v[200:203], v[220:223], v[74:77]
	v_mfma_f32_16x16x32_bf16 v[192:195], v[208:211], v[212:215], v[70:73]
	v_mfma_f32_16x16x32_bf16 v[196:199], v[208:211], v[220:223], v[66:69]
	s_setprio 0
	s_barrier
	s_nop 0
	ds_read_b128 v[66:69], v133 offset:16384
	ds_read_b128 v[70:73], v133 offset:17408
	ds_read_b128 v[74:77], v134 offset:16384
	ds_read_b128 v[78:81], v134 offset:17408
	ds_read_b128 v[82:85], v137 offset:16384
	ds_read_b128 v[94:97], v137 offset:17408
	ds_read_b128 v[200:203], v139 offset:16384
	ds_read_b128 v[204:207], v139 offset:17408
	s_waitcnt vmcnt(4)
	s_barrier
	s_waitcnt lgkmcnt(0)
	s_setprio 1
	s_waitcnt lgkmcnt(0)
	v_mfma_f32_16x16x32_bf16 v[62:65], v[66:69], v[148:151], v[62:65]
	v_mfma_f32_16x16x32_bf16 v[58:61], v[66:69], v[156:159], v[58:61]
	v_mfma_f32_16x16x32_bf16 v[54:57], v[74:77], v[148:151], v[54:57]
	v_mfma_f32_16x16x32_bf16 v[50:53], v[74:77], v[156:159], v[50:53]
	v_mfma_f32_16x16x32_bf16 v[46:49], v[82:85], v[148:151], v[46:49]
	v_mfma_f32_16x16x32_bf16 v[42:45], v[82:85], v[156:159], v[42:45]
	v_mfma_f32_16x16x32_bf16 v[38:41], v[200:203], v[148:151], v[38:41]
	v_mfma_f32_16x16x32_bf16 v[34:37], v[200:203], v[156:159], v[34:37]
	v_mfma_f32_16x16x32_bf16 v[62:65], v[70:73], v[152:155], v[62:65]
	v_mfma_f32_16x16x32_bf16 v[58:61], v[70:73], v[160:163], v[58:61]
	v_mfma_f32_16x16x32_bf16 v[54:57], v[78:81], v[152:155], v[54:57]
	v_mfma_f32_16x16x32_bf16 v[50:53], v[78:81], v[160:163], v[50:53]
	v_mfma_f32_16x16x32_bf16 v[46:49], v[94:97], v[152:155], v[46:49]
	v_mfma_f32_16x16x32_bf16 v[42:45], v[94:97], v[160:163], v[42:45]
	v_mfma_f32_16x16x32_bf16 v[38:41], v[204:207], v[152:155], v[38:41]
	v_mfma_f32_16x16x32_bf16 v[34:37], v[204:207], v[160:163], v[34:37]
	s_setprio 0
	s_setprio 1
	v_mfma_f32_16x16x32_bf16 v[30:33], v[66:69], v[114:117], v[30:33]
	v_mfma_f32_16x16x32_bf16 v[26:29], v[66:69], v[216:219], v[26:29]
	v_mfma_f32_16x16x32_bf16 v[22:25], v[74:77], v[114:117], v[22:25]
	v_mfma_f32_16x16x32_bf16 v[18:21], v[74:77], v[216:219], v[18:21]
	v_mfma_f32_16x16x32_bf16 v[14:17], v[82:85], v[114:117], v[14:17]
	v_mfma_f32_16x16x32_bf16 v[10:13], v[82:85], v[216:219], v[10:13]
	v_mfma_f32_16x16x32_bf16 v[6:9], v[200:203], v[114:117], v[6:9]
	v_mfma_f32_16x16x32_bf16 v[2:5], v[200:203], v[216:219], v[2:5]
	v_mfma_f32_16x16x32_bf16 v[148:151], v[70:73], v[212:215], v[30:33]
	v_mfma_f32_16x16x32_bf16 v[152:155], v[70:73], v[220:223], v[26:29]
	v_mfma_f32_16x16x32_bf16 v[156:159], v[78:81], v[212:215], v[22:25]
	v_mfma_f32_16x16x32_bf16 v[160:163], v[78:81], v[220:223], v[18:21]
	v_mfma_f32_16x16x32_bf16 v[208:211], v[94:97], v[212:215], v[14:17]
	v_mfma_f32_16x16x32_bf16 v[228:231], v[94:97], v[220:223], v[10:13]
	v_mfma_f32_16x16x32_bf16 v[212:215], v[204:207], v[212:215], v[6:9]
	v_mfma_f32_16x16x32_bf16 v[200:203], v[204:207], v[220:223], v[2:5]
	s_setprio 0
	s_barrier
	ds_read_b128 v[14:17], v145
	ds_read_b128 v[30:33], v145 offset:1024
	ds_read_b128 v[204:207], v145 offset:2048
	ds_read_b128 v[216:219], v145 offset:3072
	ds_read_b128 v[2:5], v133 offset:32768
	ds_read_b128 v[6:9], v133 offset:33792
	ds_read_b128 v[10:13], v134 offset:32768
	ds_read_b128 v[18:21], v134 offset:33792
	ds_read_b128 v[22:25], v137 offset:32768
	ds_read_b128 v[26:29], v137 offset:33792
	ds_read_b128 v[220:223], v139 offset:32768
	ds_read_b128 v[232:235], v139 offset:33792
	s_waitcnt vmcnt(2)
	s_barrier
; #define LDA(dst, b, h) for (int m = 0; m < 4; ++m) for (int k = 0; k < 2; ++k) \
;     dst[m][k] = *reinterpret_cast<const bf16x8*>((char*)SA(b, h) + lds_byte(wr * 64 + m * 16 + fr, k * 32 + fq * 8))
; #define LDB(dst, b, h) for (int n = 0; n < 2; ++n) for (int k = 0; k < 2; ++k) \
;     dst[n][k] = *reinterpret_cast<const bf16x8*>((char*)SB(b, h) + lds_byte(wc * 32 + n * 16 + fr, k * 32 + fq * 8))
; #define MMA(ai, bj, At, Bt_) do { __builtin_amdgcn_s_setprio(1); \
;     for (int m = 0; m < 4; ++m) for (int n = 0; n < 2; ++n) for (int k = 0; k < 2; ++k) \
;       acc[ai][bj][m][n] = __builtin_amdgcn_mfma_f32_16x16x32_bf16(At[m][k], Bt_[n][k], acc[ai][bj][m][n], 0, 0, 0); \
;     __builtin_amdgcn_s_setprio(0); } while (0)
; #define WAIT_V(n) asm volatile("s_waitcnt vmcnt(" #n ")" ::: "memory")
; #define WAIT_L(n) asm volatile("s_waitcnt lgkmcnt(" #n ")" ::: "memory")
; #define BAR __builtin_amdgcn_s_barrier()
;     ...
;     { LDB(B0, 1, 0); LDA(At, 1, 0); WAIT_V(2); BAR; WAIT_L(0); MMA(0, 0, At, B0); BAR;
;       LDB(B1, 1, 1); WAIT_V(0); BAR; WAIT_L(0); MMA(0, 1, At, B1); BAR;
;       LDA(At, 1, 1); BAR; WAIT_L(0); MMA(1, 0, At, B0); MMA(1, 1, At, B1); BAR; }
;     if (wr == 0) BAR;
	s_waitcnt lgkmcnt(0)
	s_setprio 1
	s_waitcnt lgkmcnt(0)
	v_mfma_f32_16x16x32_bf16 v[66:69], v[2:5], v[14:17], v[126:129]
	v_mfma_f32_16x16x32_bf16 v[114:117], v[6:9], v[30:33], v[66:69]
	v_mfma_f32_16x16x32_bf16 v[66:69], v[2:5], v[204:207], v[122:125]
	v_mfma_f32_16x16x32_bf16 v[126:129], v[6:9], v[216:219], v[66:69]
	v_mfma_f32_16x16x32_bf16 v[66:69], v[10:13], v[14:17], v[118:121]
	v_mfma_f32_16x16x32_bf16 v[82:85], v[18:21], v[30:33], v[66:69]
	v_mfma_f32_16x16x32_bf16 v[66:69], v[10:13], v[204:207], v[140:143]
	v_mfma_f32_16x16x32_bf16 v[94:97], v[18:21], v[216:219], v[66:69]
	v_mfma_f32_16x16x32_bf16 v[66:69], v[22:25], v[14:17], v[110:113]
	v_mfma_f32_16x16x32_bf16 v[74:77], v[26:29], v[30:33], v[66:69]
	v_mfma_f32_16x16x32_bf16 v[66:69], v[22:25], v[204:207], v[106:109]
	v_mfma_f32_16x16x32_bf16 v[78:81], v[26:29], v[216:219], v[66:69]
	v_mfma_f32_16x16x32_bf16 v[66:69], v[220:223], v[14:17], v[102:105]
	v_mfma_f32_16x16x32_bf16 v[70:73], v[220:223], v[204:207], v[98:101]
	v_mfma_f32_16x16x32_bf16 v[66:69], v[232:235], v[30:33], v[66:69]
	v_mfma_f32_16x16x32_bf16 v[70:73], v[232:235], v[216:219], v[70:73]
	s_setprio 0
	s_barrier
	ds_read_b128 v[140:143], v146
	ds_read_b128 v[236:239], v146 offset:1024
	ds_read_b128 v[240:243], v146 offset:2048
	ds_read_b128 v[144:147], v146 offset:3072
	s_waitcnt vmcnt(0)
	s_barrier
	s_waitcnt lgkmcnt(0)
	s_setprio 1
	s_waitcnt lgkmcnt(0)
	v_mfma_f32_16x16x32_bf16 v[98:101], v[2:5], v[140:143], v[224:227]
	v_mfma_f32_16x16x32_bf16 v[2:5], v[2:5], v[240:243], v[90:93]
	v_mfma_f32_16x16x32_bf16 v[118:121], v[6:9], v[144:147], v[2:5]
	v_mfma_f32_16x16x32_bf16 v[2:5], v[10:13], v[140:143], v[86:89]
	v_mfma_f32_16x16x32_bf16 v[102:105], v[18:21], v[236:239], v[2:5]
	v_mfma_f32_16x16x32_bf16 v[2:5], v[10:13], v[240:243], v[164:167]
	v_mfma_f32_16x16x32_bf16 v[122:125], v[18:21], v[144:147], v[2:5]
	v_mfma_f32_16x16x32_bf16 v[2:5], v[22:25], v[140:143], v[184:187]
	v_mfma_f32_16x16x32_bf16 v[90:93], v[26:29], v[236:239], v[2:5]
	v_mfma_f32_16x16x32_bf16 v[2:5], v[22:25], v[240:243], v[188:191]
	v_mfma_f32_16x16x32_bf16 v[110:113], v[26:29], v[144:147], v[2:5]
	v_mfma_f32_16x16x32_bf16 v[2:5], v[220:223], v[140:143], v[192:195]
	v_mfma_f32_16x16x32_bf16 v[86:89], v[232:235], v[236:239], v[2:5]
	v_mfma_f32_16x16x32_bf16 v[2:5], v[220:223], v[240:243], v[196:199]
	v_mfma_f32_16x16x32_bf16 v[98:101], v[6:9], v[236:239], v[98:101]
	v_mfma_f32_16x16x32_bf16 v[106:109], v[232:235], v[144:147], v[2:5]
	s_setprio 0
	s_barrier
	ds_read_b128 v[164:167], v133 offset:49152
	ds_read_b128 v[184:187], v133 offset:50176
	ds_read_b128 v[188:191], v134 offset:49152
	ds_read_b128 v[192:195], v134 offset:50176
	ds_read_b128 v[196:199], v137 offset:49152
	ds_read_b128 v[220:223], v137 offset:50176
	ds_read_b128 v[224:227], v139 offset:49152
	ds_read_b128 v[232:235], v139 offset:50176
	s_barrier
	s_waitcnt lgkmcnt(0)
	s_setprio 1
	s_waitcnt lgkmcnt(0)
	v_mfma_f32_16x16x32_bf16 v[6:9], v[164:167], v[204:207], v[58:61]
	v_mfma_f32_16x16x32_bf16 v[10:13], v[188:191], v[204:207], v[50:53]
	v_mfma_f32_16x16x32_bf16 v[2:5], v[164:167], v[14:17], v[62:65]
	v_mfma_f32_16x16x32_bf16 v[18:21], v[184:187], v[216:219], v[6:9]
	v_mfma_f32_16x16x32_bf16 v[6:9], v[188:191], v[14:17], v[54:57]
	v_mfma_f32_16x16x32_bf16 v[22:25], v[192:195], v[216:219], v[10:13]
	v_mfma_f32_16x16x32_bf16 v[10:13], v[196:199], v[14:17], v[46:49]
	v_mfma_f32_16x16x32_bf16 v[14:17], v[224:227], v[14:17], v[38:41]
	v_mfma_f32_16x16x32_bf16 v[2:5], v[184:187], v[30:33], v[2:5]
	v_mfma_f32_16x16x32_bf16 v[6:9], v[192:195], v[30:33], v[6:9]
	v_mfma_f32_16x16x32_bf16 v[10:13], v[220:223], v[30:33], v[10:13]
	v_mfma_f32_16x16x32_bf16 v[26:29], v[196:199], v[204:207], v[42:45]
	v_mfma_f32_16x16x32_bf16 v[14:17], v[232:235], v[30:33], v[14:17]
	v_mfma_f32_16x16x32_bf16 v[30:33], v[224:227], v[204:207], v[34:37]
	v_mfma_f32_16x16x32_bf16 v[26:29], v[220:223], v[216:219], v[26:29]
	v_mfma_f32_16x16x32_bf16 v[30:33], v[232:235], v[216:219], v[30:33]
	s_setprio 0
	s_setprio 1
	v_mfma_f32_16x16x32_bf16 v[38:41], v[164:167], v[240:243], v[152:155]
	v_mfma_f32_16x16x32_bf16 v[42:45], v[188:191], v[240:243], v[160:163]
	v_mfma_f32_16x16x32_bf16 v[46:49], v[196:199], v[240:243], v[228:231]
	v_mfma_f32_16x16x32_bf16 v[34:37], v[164:167], v[140:143], v[148:151]
	v_mfma_f32_16x16x32_bf16 v[50:53], v[184:187], v[144:147], v[38:41]
	v_mfma_f32_16x16x32_bf16 v[38:41], v[188:191], v[140:143], v[156:159]
	v_mfma_f32_16x16x32_bf16 v[54:57], v[192:195], v[144:147], v[42:45]
	v_mfma_f32_16x16x32_bf16 v[42:45], v[196:199], v[140:143], v[208:211]
	v_mfma_f32_16x16x32_bf16 v[58:61], v[220:223], v[144:147], v[46:49]
	v_mfma_f32_16x16x32_bf16 v[46:49], v[224:227], v[140:143], v[212:215]
	v_mfma_f32_16x16x32_bf16 v[62:65], v[224:227], v[240:243], v[200:203]
	v_mfma_f32_16x16x32_bf16 v[34:37], v[184:187], v[236:239], v[34:37]
	v_mfma_f32_16x16x32_bf16 v[38:41], v[192:195], v[236:239], v[38:41]
	v_mfma_f32_16x16x32_bf16 v[42:45], v[220:223], v[236:239], v[42:45]
	v_mfma_f32_16x16x32_bf16 v[46:49], v[232:235], v[236:239], v[46:49]
	v_mfma_f32_16x16x32_bf16 v[62:65], v[232:235], v[144:147], v[62:65]
	s_setprio 0
	v_readlane_b32 s4, v245, 33
	v_readlane_b32 s5, v245, 34
	s_and_b64 vcc, exec, s[4:5]
	s_barrier
	s_cbranch_vccz .LBB0_205
	s_barrier

; #define LDA(dst, b, h) for (int m = 0; m < 4; ++m) for (int k = 0; k < 2; ++k) \
;     dst[m][k] = *reinterpret_cast<const bf16x8*>((char*)SA(b, h) + lds_byte(wr * 64 + m * 16 + fr, k * 32 + fq * 8))
; #define LDB(dst, b, h) for (int n = 0; n < 2; ++n) for (int k = 0; k < 2; ++k) \
;     dst[n][k] = *reinterpret_cast<const bf16x8*>((char*)SB(b, h) + lds_byte(wc * 32 + n * 16 + fr, k * 32 + fq * 8))
; #define MMA(ai, bj, At, Bt_) do { __builtin_amdgcn_s_setprio(1); \
;     for (int m = 0; m < 4; ++m) for (int n = 0; n < 2; ++n) for (int k = 0; k < 2; ++k) \
;       acc[ai][bj][m][n] = __builtin_amdgcn_mfma_f32_16x16x32_bf16(At[m][k], Bt_[n][k], acc[ai][bj][m][n], 0, 0, 0); \
;     __builtin_amdgcn_s_setprio(0); } while (0)
; #define WAIT_L(n) asm volatile("s_waitcnt lgkmcnt(" #n ")" ::: "memory")
; #define BAR __builtin_amdgcn_s_barrier()
; #define SCHED __builtin_amdgcn_sched_barrier(0)
;     ...
;       LDB(B0, 0, 0); SCHED; LDA(At, 0, 0); STAGE(SA(1, 1), A, brow + HALF, t + 1);
;       WAIT_L(8); BAR; WAIT_L(0); MMA(0, 0, At, B0); BAR; SCHED;
;       LDB(B1, 0, 1); STAGE(SB(0, 0), Bt, bcol, t + 2);
;       BAR; WAIT_L(0); MMA(0, 1, At, B1); BAR;
;       LDA(At, 0, 1); STAGE(SA(0, 0), A, brow, t + 2);
;       BAR; WAIT_L(0); MMA(1, 0, At, B0); BAR; SCHED;
.LBB0_418:
	v_add_u32_e32 v143, s2, v142
	ds_read_b128 v[146:149], v143
	ds_read_b128 v[150:153], v143 offset:1024
	ds_read_b128 v[154:157], v143 offset:2048
	ds_read_b128 v[158:161], v143 offset:3072
	s_add_u32 s42, s30, s6
	s_addc_u32 s43, s31, s7
	s_add_u32 s44, s42, 0x80080
	s_addc_u32 s45, s43, 0
	s_add_i32 s41, s15, 0xc000
	ds_read_b128 v[162:165], v133
	ds_read_b128 v[184:187], v133 offset:1024
	ds_read_b128 v[188:191], v134
	ds_read_b128 v[192:195], v134 offset:1024
	ds_read_b128 v[196:199], v137
	ds_read_b128 v[200:203], v137 offset:1024
	ds_read_b128 v[204:207], v139
	ds_read_b128 v[208:211], v139 offset:1024
	s_mov_b32 m0, s41
	v_lshl_add_u64 v[144:145], s[44:45], 0, v[0:1]
	s_add_i32 s37, s15, 0xe000
	global_load_lds_dwordx4 v[144:145], off
	v_lshl_add_u64 v[144:145], s[44:45], 0, v[140:141]
	s_mov_b32 m0, s37
	s_nop 0
	global_load_lds_dwordx4 v[144:145], off
	s_barrier
	s_waitcnt lgkmcnt(0)
	s_waitcnt lgkmcnt(0)
	v_mfma_f32_16x16x32_bf16 v[126:129], v[162:165], v[146:149], v[126:129]
	v_mfma_f32_16x16x32_bf16 v[122:125], v[162:165], v[154:157], v[122:125]
	v_mfma_f32_16x16x32_bf16 v[118:121], v[188:191], v[146:149], v[118:121]
	v_mfma_f32_16x16x32_bf16 v[114:117], v[188:191], v[154:157], v[114:117]
	v_mfma_f32_16x16x32_bf16 v[110:113], v[196:199], v[146:149], v[110:113]
	v_mfma_f32_16x16x32_bf16 v[106:109], v[196:199], v[154:157], v[106:109]
	v_mfma_f32_16x16x32_bf16 v[102:105], v[204:207], v[146:149], v[102:105]
	v_mfma_f32_16x16x32_bf16 v[98:101], v[204:207], v[154:157], v[98:101]
	v_mfma_f32_16x16x32_bf16 v[126:129], v[184:187], v[150:153], v[126:129]
	v_mfma_f32_16x16x32_bf16 v[122:125], v[184:187], v[158:161], v[122:125]
	v_mfma_f32_16x16x32_bf16 v[118:121], v[192:195], v[150:153], v[118:121]
	v_mfma_f32_16x16x32_bf16 v[114:117], v[192:195], v[158:161], v[114:117]
	v_mfma_f32_16x16x32_bf16 v[110:113], v[200:203], v[150:153], v[110:113]
	v_mfma_f32_16x16x32_bf16 v[106:109], v[200:203], v[158:161], v[106:109]
	v_mfma_f32_16x16x32_bf16 v[102:105], v[208:211], v[150:153], v[102:105]
	v_mfma_f32_16x16x32_bf16 v[98:101], v[208:211], v[158:161], v[98:101]
	s_barrier
	s_add_u32 s44, s34, s6
	s_addc_u32 s45, s35, s7
	s_add_u32 s50, s44, 0x100
	v_add_u32_e32 v144, s76, v142
	s_addc_u32 s51, s45, 0
	s_mov_b32 m0, s23
	ds_read_b128 v[212:215], v144
	ds_read_b128 v[216:219], v144 offset:1024
	ds_read_b128 v[220:223], v144 offset:2048
	ds_read_b128 v[224:227], v144 offset:3072
	s_nop 0
	v_lshl_add_u64 v[166:167], s[50:51], 0, v[0:1]
	global_load_lds_dwordx4 v[166:167], off
	v_lshl_add_u64 v[166:167], s[50:51], 0, v[140:141]
	s_mov_b32 m0, s26
	s_nop 0
	global_load_lds_dwordx4 v[166:167], off
	s_barrier
	s_waitcnt lgkmcnt(0)
	s_waitcnt lgkmcnt(0)
	v_mfma_f32_16x16x32_bf16 v[94:97], v[162:165], v[212:215], v[94:97]
	v_mfma_f32_16x16x32_bf16 v[90:93], v[162:165], v[220:223], v[90:93]
	v_mfma_f32_16x16x32_bf16 v[86:89], v[188:191], v[212:215], v[86:89]
	v_mfma_f32_16x16x32_bf16 v[82:85], v[188:191], v[220:223], v[82:85]
	v_mfma_f32_16x16x32_bf16 v[78:81], v[196:199], v[212:215], v[78:81]
	v_mfma_f32_16x16x32_bf16 v[74:77], v[196:199], v[220:223], v[74:77]
	v_mfma_f32_16x16x32_bf16 v[70:73], v[204:207], v[212:215], v[70:73]
	v_mfma_f32_16x16x32_bf16 v[66:69], v[204:207], v[220:223], v[66:69]
	v_mfma_f32_16x16x32_bf16 v[94:97], v[184:187], v[216:219], v[94:97]
	v_mfma_f32_16x16x32_bf16 v[90:93], v[184:187], v[224:227], v[90:93]
	v_mfma_f32_16x16x32_bf16 v[86:89], v[192:195], v[216:219], v[86:89]
	v_mfma_f32_16x16x32_bf16 v[82:85], v[192:195], v[224:227], v[82:85]
	v_mfma_f32_16x16x32_bf16 v[78:81], v[200:203], v[216:219], v[78:81]
	v_mfma_f32_16x16x32_bf16 v[74:77], v[200:203], v[224:227], v[74:77]
	v_mfma_f32_16x16x32_bf16 v[70:73], v[208:211], v[216:219], v[70:73]
	v_mfma_f32_16x16x32_bf16 v[66:69], v[208:211], v[224:227], v[66:69]
	s_add_u32 s50, s42, 0x100
	s_addc_u32 s51, s43, 0
	s_mov_b32 m0, s15
	s_barrier
	ds_read_b128 v[162:165], v133 offset:16384
	ds_read_b128 v[184:187], v133 offset:17408
	ds_read_b128 v[188:191], v134 offset:16384
	ds_read_b128 v[192:195], v134 offset:17408
	ds_read_b128 v[196:199], v137 offset:16384
	ds_read_b128 v[200:203], v137 offset:17408
	ds_read_b128 v[204:207], v139 offset:16384
	ds_read_b128 v[208:211], v139 offset:17408
	s_nop 0
	v_lshl_add_u64 v[166:167], s[50:51], 0, v[0:1]
	global_load_lds_dwordx4 v[166:167], off
	v_lshl_add_u64 v[166:167], s[50:51], 0, v[140:141]
	s_mov_b32 m0, s25
	s_nop 0
	global_load_lds_dwordx4 v[166:167], off
	s_barrier
	s_waitcnt lgkmcnt(0)
	s_waitcnt lgkmcnt(0)
	v_mfma_f32_16x16x32_bf16 v[62:65], v[162:165], v[146:149], v[62:65]
	v_mfma_f32_16x16x32_bf16 v[58:61], v[162:165], v[154:157], v[58:61]
	v_mfma_f32_16x16x32_bf16 v[54:57], v[188:191], v[146:149], v[54:57]
	v_mfma_f32_16x16x32_bf16 v[50:53], v[188:191], v[154:157], v[50:53]
	v_mfma_f32_16x16x32_bf16 v[46:49], v[196:199], v[146:149], v[46:49]
	v_mfma_f32_16x16x32_bf16 v[42:45], v[196:199], v[154:157], v[42:45]
	v_mfma_f32_16x16x32_bf16 v[38:41], v[204:207], v[146:149], v[38:41]
	v_mfma_f32_16x16x32_bf16 v[34:37], v[204:207], v[154:157], v[34:37]
	v_mfma_f32_16x16x32_bf16 v[62:65], v[184:187], v[150:153], v[62:65]
	v_mfma_f32_16x16x32_bf16 v[58:61], v[184:187], v[158:161], v[58:61]
	v_mfma_f32_16x16x32_bf16 v[54:57], v[192:195], v[150:153], v[54:57]
	v_mfma_f32_16x16x32_bf16 v[50:53], v[192:195], v[158:161], v[50:53]
	v_mfma_f32_16x16x32_bf16 v[46:49], v[200:203], v[150:153], v[46:49]
	v_mfma_f32_16x16x32_bf16 v[42:45], v[200:203], v[158:161], v[42:45]
	v_mfma_f32_16x16x32_bf16 v[38:41], v[208:211], v[150:153], v[38:41]
	v_mfma_f32_16x16x32_bf16 v[34:37], v[208:211], v[158:161], v[34:37]
	s_barrier
; #define LDA(dst, b, h) for (int m = 0; m < 4; ++m) for (int k = 0; k < 2; ++k) \
;     dst[m][k] = *reinterpret_cast<const bf16x8*>((char*)SA(b, h) + lds_byte(wr * 64 + m * 16 + fr, k * 32 + fq * 8))
; #define LDB(dst, b, h) for (int n = 0; n < 2; ++n) for (int k = 0; k < 2; ++k) \
;     dst[n][k] = *reinterpret_cast<const bf16x8*>((char*)SB(b, h) + lds_byte(wc * 32 + n * 16 + fr, k * 32 + fq * 8))
; #define MMA(ai, bj, At, Bt_) do { __builtin_amdgcn_s_setprio(1); \
;     for (int m = 0; m < 4; ++m) for (int n = 0; n < 2; ++n) for (int k = 0; k < 2; ++k) \
;       acc[ai][bj][m][n] = __builtin_amdgcn_mfma_f32_16x16x32_bf16(At[m][k], Bt_[n][k], acc[ai][bj][m][n], 0, 0, 0); \
;     __builtin_amdgcn_s_setprio(0); } while (0)
; #define WAIT_V(n) asm volatile("s_waitcnt vmcnt(" #n ")" ::: "memory")
; #define WAIT_L(n) asm volatile("s_waitcnt lgkmcnt(" #n ")" ::: "memory")
; #define BAR __builtin_amdgcn_s_barrier()
; #define SCHED __builtin_amdgcn_sched_barrier(0)
;     ...
;       STAGE(SB(0, 1), Bt, bcol + HALF, t + 2);
;       WAIT_V(6); BAR; MMA(1, 1, At, B1); BAR;
;       LDB(B0, 1, 0); SCHED; LDA(At, 1, 0); STAGE(SA(0, 1), A, brow + HALF, t + 2);
;       WAIT_L(8); BAR; WAIT_L(0); MMA(0, 0, At, B0); BAR; SCHED;
;       LDB(B1, 1, 1); STAGE(SB(1, 0), Bt, bcol, t + 3);
;       BAR; WAIT_L(0); MMA(0, 1, At, B1); BAR;
;       LDA(At, 1, 1); STAGE(SA(1, 0), A, brow, t + 3);
	s_add_u32 s50, s44, 0x80100
	s_addc_u32 s51, s45, 0
	s_mov_b32 m0, s27
	s_nop 0
	v_lshl_add_u64 v[146:147], s[50:51], 0, v[0:1]
	global_load_lds_dwordx4 v[146:147], off
	v_lshl_add_u64 v[146:147], s[50:51], 0, v[140:141]
	s_mov_b32 m0, s28
	s_nop 0
	global_load_lds_dwordx4 v[146:147], off
	s_waitcnt vmcnt(6)
	s_barrier
	v_mfma_f32_16x16x32_bf16 v[30:33], v[162:165], v[212:215], v[30:33]
	v_mfma_f32_16x16x32_bf16 v[26:29], v[162:165], v[220:223], v[26:29]
	v_mfma_f32_16x16x32_bf16 v[22:25], v[188:191], v[212:215], v[22:25]
	v_mfma_f32_16x16x32_bf16 v[18:21], v[188:191], v[220:223], v[18:21]
	v_mfma_f32_16x16x32_bf16 v[14:17], v[196:199], v[212:215], v[14:17]
	v_mfma_f32_16x16x32_bf16 v[10:13], v[196:199], v[220:223], v[10:13]
	v_mfma_f32_16x16x32_bf16 v[6:9], v[204:207], v[212:215], v[6:9]
	v_mfma_f32_16x16x32_bf16 v[2:5], v[204:207], v[220:223], v[2:5]
	v_mfma_f32_16x16x32_bf16 v[30:33], v[184:187], v[216:219], v[30:33]
	v_mfma_f32_16x16x32_bf16 v[26:29], v[184:187], v[224:227], v[26:29]
	v_mfma_f32_16x16x32_bf16 v[22:25], v[192:195], v[216:219], v[22:25]
	v_mfma_f32_16x16x32_bf16 v[18:21], v[192:195], v[224:227], v[18:21]
	v_mfma_f32_16x16x32_bf16 v[14:17], v[200:203], v[216:219], v[14:17]
	v_mfma_f32_16x16x32_bf16 v[10:13], v[200:203], v[224:227], v[10:13]
	v_mfma_f32_16x16x32_bf16 v[6:9], v[208:211], v[216:219], v[6:9]
	v_mfma_f32_16x16x32_bf16 v[2:5], v[208:211], v[224:227], v[2:5]
	v_add_u32_e32 v145, s77, v142
	s_barrier
	ds_read_b128 v[148:151], v145
	ds_read_b128 v[152:155], v145 offset:1024
	ds_read_b128 v[156:159], v145 offset:2048
	ds_read_b128 v[160:163], v145 offset:3072
	s_add_u32 s50, s42, 0x80100
	s_addc_u32 s51, s43, 0
	s_mov_b32 m0, s17
	ds_read_b128 v[164:167], v133 offset:32768
	ds_read_b128 v[184:187], v133 offset:33792
	ds_read_b128 v[188:191], v134 offset:32768
	ds_read_b128 v[192:195], v134 offset:33792
	ds_read_b128 v[196:199], v137 offset:32768
	ds_read_b128 v[200:203], v137 offset:33792
	ds_read_b128 v[204:207], v139 offset:32768
	ds_read_b128 v[208:211], v139 offset:33792
	s_nop 0
	v_lshl_add_u64 v[146:147], s[50:51], 0, v[0:1]
	global_load_lds_dwordx4 v[146:147], off
	v_lshl_add_u64 v[146:147], s[50:51], 0, v[140:141]
	s_mov_b32 m0, s29
	s_nop 0
	global_load_lds_dwordx4 v[146:147], off
	s_barrier
	s_waitcnt lgkmcnt(0)
	s_waitcnt lgkmcnt(0)
	v_mfma_f32_16x16x32_bf16 v[126:129], v[164:167], v[148:151], v[126:129]
	v_mfma_f32_16x16x32_bf16 v[122:125], v[164:167], v[156:159], v[122:125]
	v_mfma_f32_16x16x32_bf16 v[118:121], v[188:191], v[148:151], v[118:121]
	v_mfma_f32_16x16x32_bf16 v[114:117], v[188:191], v[156:159], v[114:117]
	v_mfma_f32_16x16x32_bf16 v[110:113], v[196:199], v[148:151], v[110:113]
	v_mfma_f32_16x16x32_bf16 v[106:109], v[196:199], v[156:159], v[106:109]
	v_mfma_f32_16x16x32_bf16 v[102:105], v[204:207], v[148:151], v[102:105]
	v_mfma_f32_16x16x32_bf16 v[98:101], v[204:207], v[156:159], v[98:101]
	v_mfma_f32_16x16x32_bf16 v[126:129], v[184:187], v[152:155], v[126:129]
	v_mfma_f32_16x16x32_bf16 v[122:125], v[184:187], v[160:163], v[122:125]
	v_mfma_f32_16x16x32_bf16 v[118:121], v[192:195], v[152:155], v[118:121]
	v_mfma_f32_16x16x32_bf16 v[114:117], v[192:195], v[160:163], v[114:117]
	v_mfma_f32_16x16x32_bf16 v[110:113], v[200:203], v[152:155], v[110:113]
	v_mfma_f32_16x16x32_bf16 v[106:109], v[200:203], v[160:163], v[106:109]
	v_mfma_f32_16x16x32_bf16 v[102:105], v[208:211], v[152:155], v[102:105]
	v_mfma_f32_16x16x32_bf16 v[98:101], v[208:211], v[160:163], v[98:101]
	s_barrier
	s_add_u32 s50, s44, 0x180
	v_add_u32_e32 v146, s78, v142
	s_addc_u32 s51, s45, 0
	s_mov_b32 m0, s8
	ds_read_b128 v[212:215], v146
	ds_read_b128 v[216:219], v146 offset:1024
	ds_read_b128 v[220:223], v146 offset:2048
	ds_read_b128 v[224:227], v146 offset:3072
	s_nop 0
	v_lshl_add_u64 v[228:229], s[50:51], 0, v[0:1]
	global_load_lds_dwordx4 v[228:229], off
	v_lshl_add_u64 v[228:229], s[50:51], 0, v[140:141]
	s_mov_b32 m0, s9
	s_nop 0
	global_load_lds_dwordx4 v[228:229], off
	s_barrier
	s_waitcnt lgkmcnt(0)
	s_waitcnt lgkmcnt(0)
	v_mfma_f32_16x16x32_bf16 v[94:97], v[164:167], v[212:215], v[94:97]
	v_mfma_f32_16x16x32_bf16 v[90:93], v[164:167], v[220:223], v[90:93]
	v_mfma_f32_16x16x32_bf16 v[86:89], v[188:191], v[212:215], v[86:89]
	v_mfma_f32_16x16x32_bf16 v[82:85], v[188:191], v[220:223], v[82:85]
	v_mfma_f32_16x16x32_bf16 v[78:81], v[196:199], v[212:215], v[78:81]
	v_mfma_f32_16x16x32_bf16 v[74:77], v[196:199], v[220:223], v[74:77]
	v_mfma_f32_16x16x32_bf16 v[70:73], v[204:207], v[212:215], v[70:73]
	v_mfma_f32_16x16x32_bf16 v[66:69], v[204:207], v[220:223], v[66:69]
	v_mfma_f32_16x16x32_bf16 v[94:97], v[184:187], v[216:219], v[94:97]
	v_mfma_f32_16x16x32_bf16 v[90:93], v[184:187], v[224:227], v[90:93]
	v_mfma_f32_16x16x32_bf16 v[86:89], v[192:195], v[216:219], v[86:89]
	v_mfma_f32_16x16x32_bf16 v[82:85], v[192:195], v[224:227], v[82:85]
	v_mfma_f32_16x16x32_bf16 v[78:81], v[200:203], v[216:219], v[78:81]
	v_mfma_f32_16x16x32_bf16 v[74:77], v[200:203], v[224:227], v[74:77]
	v_mfma_f32_16x16x32_bf16 v[70:73], v[208:211], v[216:219], v[70:73]
	v_mfma_f32_16x16x32_bf16 v[66:69], v[208:211], v[224:227], v[66:69]
	s_add_u32 s42, s42, 0x180
	s_addc_u32 s43, s43, 0
	s_mov_b32 m0, s18
	s_barrier
	ds_read_b128 v[164:167], v133 offset:49152
	ds_read_b128 v[184:187], v133 offset:50176
	ds_read_b128 v[188:191], v134 offset:49152
	ds_read_b128 v[192:195], v134 offset:50176
	ds_read_b128 v[196:199], v137 offset:49152
	ds_read_b128 v[200:203], v137 offset:50176
	ds_read_b128 v[204:207], v139 offset:49152
	ds_read_b128 v[208:211], v139 offset:50176
	s_nop 0
	v_lshl_add_u64 v[228:229], s[42:43], 0, v[0:1]
	global_load_lds_dwordx4 v[228:229], off
	v_lshl_add_u64 v[228:229], s[42:43], 0, v[140:141]
	s_mov_b32 m0, s19
	s_nop 0
	global_load_lds_dwordx4 v[228:229], off
	s_barrier
; #define LDA(dst, b, h) for (int m = 0; m < 4; ++m) for (int k = 0; k < 2; ++k) \
;     dst[m][k] = *reinterpret_cast<const bf16x8*>((char*)SA(b, h) + lds_byte(wr * 64 + m * 16 + fr, k * 32 + fq * 8))
; #define LDB(dst, b, h) for (int n = 0; n < 2; ++n) for (int k = 0; k < 2; ++k) \
;     dst[n][k] = *reinterpret_cast<const bf16x8*>((char*)SB(b, h) + lds_byte(wc * 32 + n * 16 + fr, k * 32 + fq * 8))
; #define MMA(ai, bj, At, Bt_) do { __builtin_amdgcn_s_setprio(1); \
;     for (int m = 0; m < 4; ++m) for (int n = 0; n < 2; ++n) for (int k = 0; k < 2; ++k) \
;       acc[ai][bj][m][n] = __builtin_amdgcn_mfma_f32_16x16x32_bf16(At[m][k], Bt_[n][k], acc[ai][bj][m][n], 0, 0, 0); \
;     __builtin_amdgcn_s_setprio(0); } while (0)
; #define WAIT_V(n) asm volatile("s_waitcnt vmcnt(" #n ")" ::: "memory")
; #define WAIT_L(n) asm volatile("s_waitcnt lgkmcnt(" #n ")" ::: "memory")
; #define BAR __builtin_amdgcn_s_barrier()
; #define SCHED __builtin_amdgcn_sched_barrier(0)
;     ...
;       BAR; WAIT_L(0); MMA(1, 0, At, B0); BAR; SCHED;
;       STAGE(SB(1, 1), Bt, bcol + HALF, t + 3);
;       WAIT_V(6); BAR; MMA(1, 1, At, B1); BAR;
;     }
;     { LDB(B0, 0, 0); LDA(At, 0, 0); STAGE(SA(1, 1), A, brow + HALF, nt - 1);
;       BAR; WAIT_L(0); MMA(0, 0, At, B0); BAR;
;       LDB(B1, 0, 1); BAR; WAIT_L(0); MMA(0, 1, At, B1); BAR;
	s_waitcnt lgkmcnt(0)
	s_waitcnt lgkmcnt(0)
	v_mfma_f32_16x16x32_bf16 v[62:65], v[164:167], v[148:151], v[62:65]
	v_mfma_f32_16x16x32_bf16 v[58:61], v[164:167], v[156:159], v[58:61]
	v_mfma_f32_16x16x32_bf16 v[54:57], v[188:191], v[148:151], v[54:57]
	v_mfma_f32_16x16x32_bf16 v[50:53], v[188:191], v[156:159], v[50:53]
	v_mfma_f32_16x16x32_bf16 v[46:49], v[196:199], v[148:151], v[46:49]
	v_mfma_f32_16x16x32_bf16 v[42:45], v[196:199], v[156:159], v[42:45]
	v_mfma_f32_16x16x32_bf16 v[38:41], v[204:207], v[148:151], v[38:41]
	v_mfma_f32_16x16x32_bf16 v[34:37], v[204:207], v[156:159], v[34:37]
	v_mfma_f32_16x16x32_bf16 v[62:65], v[184:187], v[152:155], v[62:65]
	v_mfma_f32_16x16x32_bf16 v[58:61], v[184:187], v[160:163], v[58:61]
	v_mfma_f32_16x16x32_bf16 v[54:57], v[192:195], v[152:155], v[54:57]
	v_mfma_f32_16x16x32_bf16 v[50:53], v[192:195], v[160:163], v[50:53]
	v_mfma_f32_16x16x32_bf16 v[46:49], v[200:203], v[152:155], v[46:49]
	v_mfma_f32_16x16x32_bf16 v[42:45], v[200:203], v[160:163], v[42:45]
	v_mfma_f32_16x16x32_bf16 v[38:41], v[208:211], v[152:155], v[38:41]
	v_mfma_f32_16x16x32_bf16 v[34:37], v[208:211], v[160:163], v[34:37]
	s_barrier
	s_add_u32 s42, s44, 0x80180
	s_addc_u32 s43, s45, 0
	s_mov_b32 m0, s20
	s_nop 0
	v_lshl_add_u64 v[148:149], s[42:43], 0, v[0:1]
	global_load_lds_dwordx4 v[148:149], off
	v_lshl_add_u64 v[148:149], s[42:43], 0, v[140:141]
	s_mov_b32 m0, s21
	s_nop 0
	global_load_lds_dwordx4 v[148:149], off
	s_waitcnt vmcnt(6)
	s_barrier
	v_mfma_f32_16x16x32_bf16 v[30:33], v[164:167], v[212:215], v[30:33]
	v_mfma_f32_16x16x32_bf16 v[26:29], v[164:167], v[220:223], v[26:29]
	v_mfma_f32_16x16x32_bf16 v[22:25], v[188:191], v[212:215], v[22:25]
	v_mfma_f32_16x16x32_bf16 v[18:21], v[188:191], v[220:223], v[18:21]
	v_mfma_f32_16x16x32_bf16 v[14:17], v[196:199], v[212:215], v[14:17]
	v_mfma_f32_16x16x32_bf16 v[10:13], v[196:199], v[220:223], v[10:13]
	v_mfma_f32_16x16x32_bf16 v[6:9], v[204:207], v[212:215], v[6:9]
	v_mfma_f32_16x16x32_bf16 v[2:5], v[204:207], v[220:223], v[2:5]
	v_mfma_f32_16x16x32_bf16 v[30:33], v[184:187], v[216:219], v[30:33]
	v_mfma_f32_16x16x32_bf16 v[26:29], v[184:187], v[224:227], v[26:29]
	v_mfma_f32_16x16x32_bf16 v[22:25], v[192:195], v[216:219], v[22:25]
	v_mfma_f32_16x16x32_bf16 v[18:21], v[192:195], v[224:227], v[18:21]
	v_mfma_f32_16x16x32_bf16 v[14:17], v[200:203], v[216:219], v[14:17]
	v_mfma_f32_16x16x32_bf16 v[10:13], v[200:203], v[224:227], v[10:13]
	v_mfma_f32_16x16x32_bf16 v[6:9], v[208:211], v[216:219], v[6:9]
	v_mfma_f32_16x16x32_bf16 v[2:5], v[208:211], v[224:227], v[2:5]
	s_add_i32 s36, s36, 2
	s_add_u32 s6, s6, 0x100
	s_addc_u32 s7, s7, 0
	s_cmp_gt_u32 s36, 27
	s_barrier
	s_cbranch_scc0 .LBB0_418
	s_add_u32 s4, s4, 0xf80
	s_addc_u32 s5, s5, 0
	s_mov_b32 m0, s41
	ds_read_b128 v[148:151], v143
	ds_read_b128 v[152:155], v143 offset:1024
	ds_read_b128 v[156:159], v143 offset:2048
	ds_read_b128 v[160:163], v143 offset:3072
	ds_read_b128 v[164:167], v133
	ds_read_b128 v[184:187], v133 offset:1024
	ds_read_b128 v[188:191], v134
	ds_read_b128 v[192:195], v134 offset:1024
	ds_read_b128 v[196:199], v137
	ds_read_b128 v[200:203], v137 offset:1024
	ds_read_b128 v[204:207], v139
	ds_read_b128 v[208:211], v139 offset:1024
	s_nop 0
	v_lshl_add_u64 v[142:143], s[4:5], 0, v[0:1]
	global_load_lds_dwordx4 v[142:143], off
	v_lshl_add_u64 v[140:141], s[4:5], 0, v[140:141]
	s_mov_b32 m0, s37
	s_nop 0
	global_load_lds_dwordx4 v[140:141], off
	s_barrier
	s_waitcnt lgkmcnt(0)
	s_setprio 1
	s_waitcnt lgkmcnt(0)
	v_mfma_f32_16x16x32_bf16 v[126:129], v[164:167], v[148:151], v[126:129]
	v_mfma_f32_16x16x32_bf16 v[122:125], v[164:167], v[156:159], v[122:125]
	v_mfma_f32_16x16x32_bf16 v[118:121], v[188:191], v[148:151], v[118:121]
	v_mfma_f32_16x16x32_bf16 v[110:113], v[196:199], v[148:151], v[110:113]
	v_mfma_f32_16x16x32_bf16 v[106:109], v[196:199], v[156:159], v[106:109]
	v_mfma_f32_16x16x32_bf16 v[102:105], v[204:207], v[148:151], v[102:105]
	v_mfma_f32_16x16x32_bf16 v[98:101], v[204:207], v[156:159], v[98:101]
	v_mfma_f32_16x16x32_bf16 v[126:129], v[184:187], v[152:155], v[126:129]
	v_mfma_f32_16x16x32_bf16 v[122:125], v[184:187], v[160:163], v[122:125]
	v_mfma_f32_16x16x32_bf16 v[118:121], v[192:195], v[152:155], v[118:121]
	v_mfma_f32_16x16x32_bf16 v[114:117], v[188:191], v[156:159], v[114:117]
	v_mfma_f32_16x16x32_bf16 v[110:113], v[200:203], v[152:155], v[110:113]
	v_mfma_f32_16x16x32_bf16 v[106:109], v[200:203], v[160:163], v[106:109]
	v_mfma_f32_16x16x32_bf16 v[102:105], v[208:211], v[152:155], v[102:105]
	v_mfma_f32_16x16x32_bf16 v[98:101], v[208:211], v[160:163], v[98:101]
	v_mfma_f32_16x16x32_bf16 v[140:143], v[192:195], v[160:163], v[114:117]
	s_setprio 0
	s_barrier
	s_nop 0
	ds_read_b128 v[114:117], v144
	ds_read_b128 v[212:215], v144 offset:1024
	ds_read_b128 v[216:219], v144 offset:2048
	ds_read_b128 v[220:223], v144 offset:3072
	s_barrier
	s_waitcnt lgkmcnt(0)
	s_setprio 1
	s_waitcnt lgkmcnt(0)
	v_mfma_f32_16x16x32_bf16 v[90:93], v[164:167], v[216:219], v[90:93]
	v_mfma_f32_16x16x32_bf16 v[86:89], v[188:191], v[114:117], v[86:89]
	v_mfma_f32_16x16x32_bf16 v[94:97], v[164:167], v[114:117], v[94:97]
	v_mfma_f32_16x16x32_bf16 v[90:93], v[184:187], v[220:223], v[90:93]
	v_mfma_f32_16x16x32_bf16 v[86:89], v[192:195], v[212:215], v[86:89]
	v_mfma_f32_16x16x32_bf16 v[82:85], v[188:191], v[216:219], v[82:85]
	v_mfma_f32_16x16x32_bf16 v[78:81], v[196:199], v[114:117], v[78:81]
	v_mfma_f32_16x16x32_bf16 v[74:77], v[196:199], v[216:219], v[74:77]
	v_mfma_f32_16x16x32_bf16 v[70:73], v[204:207], v[114:117], v[70:73]
	v_mfma_f32_16x16x32_bf16 v[66:69], v[204:207], v[216:219], v[66:69]
	v_mfma_f32_16x16x32_bf16 v[224:227], v[184:187], v[212:215], v[94:97]
	v_mfma_f32_16x16x32_bf16 v[164:167], v[192:195], v[220:223], v[82:85]
	v_mfma_f32_16x16x32_bf16 v[184:187], v[200:203], v[212:215], v[78:81]
	v_mfma_f32_16x16x32_bf16 v[188:191], v[200:203], v[220:223], v[74:77]
	v_mfma_f32_16x16x32_bf16 v[192:195], v[208:211], v[212:215], v[70:73]
	v_mfma_f32_16x16x32_bf16 v[196:199], v[208:211], v[220:223], v[66:69]
	s_setprio 0
	s_barrier
; #define LDA(dst, b, h) for (int m = 0; m < 4; ++m) for (int k = 0; k < 2; ++k) \
;     dst[m][k] = *reinterpret_cast<const bf16x8*>((char*)SA(b, h) + lds_byte(wr * 64 + m * 16 + fr, k * 32 + fq * 8))
; #define LDB(dst, b, h) for (int n = 0; n < 2; ++n) for (int k = 0; k < 2; ++k) \
;     dst[n][k] = *reinterpret_cast<const bf16x8*>((char*)SB(b, h) + lds_byte(wc * 32 + n * 16 + fr, k * 32 + fq * 8))
; #define MMA(ai, bj, At, Bt_) do { __builtin_amdgcn_s_setprio(1); \
;     for (int m = 0; m < 4; ++m) for (int n = 0; n < 2; ++n) for (int k = 0; k < 2; ++k) \
;       acc[ai][bj][m][n] = __builtin_amdgcn_mfma_f32_16x16x32_bf16(At[m][k], Bt_[n][k], acc[ai][bj][m][n], 0, 0, 0); \
;     __builtin_amdgcn_s_setprio(0); } while (0)
; #define WAIT_V(n) asm volatile("s_waitcnt vmcnt(" #n ")" ::: "memory")
; #define WAIT_L(n) asm volatile("s_waitcnt lgkmcnt(" #n ")" ::: "memory")
; #define BAR __builtin_amdgcn_s_barrier()
;     ...
;       LDA(At, 0, 1); WAIT_V(4); BAR; WAIT_L(0); MMA(1, 0, At, B0); MMA(1, 1, At, B1); BAR; }
;     { LDB(B0, 1, 0); LDA(At, 1, 0); WAIT_V(2); BAR; WAIT_L(0); MMA(0, 0, At, B0); BAR;
	s_nop 0
	ds_read_b128 v[66:69], v133 offset:16384
	ds_read_b128 v[70:73], v133 offset:17408
	ds_read_b128 v[74:77], v134 offset:16384
	ds_read_b128 v[78:81], v134 offset:17408
	ds_read_b128 v[82:85], v137 offset:16384
	ds_read_b128 v[94:97], v137 offset:17408
	ds_read_b128 v[200:203], v139 offset:16384
	ds_read_b128 v[204:207], v139 offset:17408
	s_waitcnt vmcnt(4)
	s_barrier
	s_waitcnt lgkmcnt(0)
	s_setprio 1
	s_waitcnt lgkmcnt(0)
	v_mfma_f32_16x16x32_bf16 v[62:65], v[66:69], v[148:151], v[62:65]
	v_mfma_f32_16x16x32_bf16 v[58:61], v[66:69], v[156:159], v[58:61]
	v_mfma_f32_16x16x32_bf16 v[54:57], v[74:77], v[148:151], v[54:57]
	v_mfma_f32_16x16x32_bf16 v[50:53], v[74:77], v[156:159], v[50:53]
	v_mfma_f32_16x16x32_bf16 v[46:49], v[82:85], v[148:151], v[46:49]
	v_mfma_f32_16x16x32_bf16 v[42:45], v[82:85], v[156:159], v[42:45]
	v_mfma_f32_16x16x32_bf16 v[38:41], v[200:203], v[148:151], v[38:41]
	v_mfma_f32_16x16x32_bf16 v[34:37], v[200:203], v[156:159], v[34:37]
	v_mfma_f32_16x16x32_bf16 v[62:65], v[70:73], v[152:155], v[62:65]
	v_mfma_f32_16x16x32_bf16 v[58:61], v[70:73], v[160:163], v[58:61]
	v_mfma_f32_16x16x32_bf16 v[54:57], v[78:81], v[152:155], v[54:57]
	v_mfma_f32_16x16x32_bf16 v[50:53], v[78:81], v[160:163], v[50:53]
	v_mfma_f32_16x16x32_bf16 v[46:49], v[94:97], v[152:155], v[46:49]
	v_mfma_f32_16x16x32_bf16 v[42:45], v[94:97], v[160:163], v[42:45]
	v_mfma_f32_16x16x32_bf16 v[38:41], v[204:207], v[152:155], v[38:41]
	v_mfma_f32_16x16x32_bf16 v[34:37], v[204:207], v[160:163], v[34:37]
	s_setprio 0
	s_setprio 1
	v_mfma_f32_16x16x32_bf16 v[30:33], v[66:69], v[114:117], v[30:33]
	v_mfma_f32_16x16x32_bf16 v[26:29], v[66:69], v[216:219], v[26:29]
	v_mfma_f32_16x16x32_bf16 v[22:25], v[74:77], v[114:117], v[22:25]
	v_mfma_f32_16x16x32_bf16 v[18:21], v[74:77], v[216:219], v[18:21]
	v_mfma_f32_16x16x32_bf16 v[14:17], v[82:85], v[114:117], v[14:17]
	v_mfma_f32_16x16x32_bf16 v[10:13], v[82:85], v[216:219], v[10:13]
	v_mfma_f32_16x16x32_bf16 v[6:9], v[200:203], v[114:117], v[6:9]
	v_mfma_f32_16x16x32_bf16 v[2:5], v[200:203], v[216:219], v[2:5]
	v_mfma_f32_16x16x32_bf16 v[148:151], v[70:73], v[212:215], v[30:33]
	v_mfma_f32_16x16x32_bf16 v[152:155], v[70:73], v[220:223], v[26:29]
	v_mfma_f32_16x16x32_bf16 v[156:159], v[78:81], v[212:215], v[22:25]
	v_mfma_f32_16x16x32_bf16 v[160:163], v[78:81], v[220:223], v[18:21]
	v_mfma_f32_16x16x32_bf16 v[208:211], v[94:97], v[212:215], v[14:17]
	v_mfma_f32_16x16x32_bf16 v[228:231], v[94:97], v[220:223], v[10:13]
	v_mfma_f32_16x16x32_bf16 v[212:215], v[204:207], v[212:215], v[6:9]
	v_mfma_f32_16x16x32_bf16 v[200:203], v[204:207], v[220:223], v[2:5]
	s_setprio 0
	s_barrier
	ds_read_b128 v[14:17], v145
	ds_read_b128 v[30:33], v145 offset:1024
	ds_read_b128 v[204:207], v145 offset:2048
	ds_read_b128 v[216:219], v145 offset:3072
	ds_read_b128 v[2:5], v133 offset:32768
	ds_read_b128 v[6:9], v133 offset:33792
	ds_read_b128 v[10:13], v134 offset:32768
	ds_read_b128 v[18:21], v134 offset:33792
	ds_read_b128 v[22:25], v137 offset:32768
	ds_read_b128 v[26:29], v137 offset:33792
	ds_read_b128 v[220:223], v139 offset:32768
	ds_read_b128 v[232:235], v139 offset:33792
	s_waitcnt vmcnt(2)
	s_barrier
	s_waitcnt lgkmcnt(0)
	s_setprio 1
	s_waitcnt lgkmcnt(0)
	v_mfma_f32_16x16x32_bf16 v[66:69], v[2:5], v[14:17], v[126:129]
	v_mfma_f32_16x16x32_bf16 v[114:117], v[6:9], v[30:33], v[66:69]
	v_mfma_f32_16x16x32_bf16 v[66:69], v[2:5], v[204:207], v[122:125]
	v_mfma_f32_16x16x32_bf16 v[126:129], v[6:9], v[216:219], v[66:69]
	v_mfma_f32_16x16x32_bf16 v[66:69], v[10:13], v[14:17], v[118:121]
	v_mfma_f32_16x16x32_bf16 v[82:85], v[18:21], v[30:33], v[66:69]
	v_mfma_f32_16x16x32_bf16 v[66:69], v[10:13], v[204:207], v[140:143]
	v_mfma_f32_16x16x32_bf16 v[94:97], v[18:21], v[216:219], v[66:69]
	v_mfma_f32_16x16x32_bf16 v[66:69], v[22:25], v[14:17], v[110:113]
	v_mfma_f32_16x16x32_bf16 v[74:77], v[26:29], v[30:33], v[66:69]
	v_mfma_f32_16x16x32_bf16 v[66:69], v[22:25], v[204:207], v[106:109]
	v_mfma_f32_16x16x32_bf16 v[78:81], v[26:29], v[216:219], v[66:69]
	v_mfma_f32_16x16x32_bf16 v[66:69], v[220:223], v[14:17], v[102:105]
	v_mfma_f32_16x16x32_bf16 v[70:73], v[220:223], v[204:207], v[98:101]
	v_mfma_f32_16x16x32_bf16 v[66:69], v[232:235], v[30:33], v[66:69]
	v_mfma_f32_16x16x32_bf16 v[70:73], v[232:235], v[216:219], v[70:73]
	s_setprio 0
	s_barrier
; #define LDA(dst, b, h) for (int m = 0; m < 4; ++m) for (int k = 0; k < 2; ++k) \
;     dst[m][k] = *reinterpret_cast<const bf16x8*>((char*)SA(b, h) + lds_byte(wr * 64 + m * 16 + fr, k * 32 + fq * 8))
; #define LDB(dst, b, h) for (int n = 0; n < 2; ++n) for (int k = 0; k < 2; ++k) \
;     dst[n][k] = *reinterpret_cast<const bf16x8*>((char*)SB(b, h) + lds_byte(wc * 32 + n * 16 + fr, k * 32 + fq * 8))
; #define MMA(ai, bj, At, Bt_) do { __builtin_amdgcn_s_setprio(1); \
;     for (int m = 0; m < 4; ++m) for (int n = 0; n < 2; ++n) for (int k = 0; k < 2; ++k) \
;       acc[ai][bj][m][n] = __builtin_amdgcn_mfma_f32_16x16x32_bf16(At[m][k], Bt_[n][k], acc[ai][bj][m][n], 0, 0, 0); \
;     __builtin_amdgcn_s_setprio(0); } while (0)
; #define WAIT_V(n) asm volatile("s_waitcnt vmcnt(" #n ")" ::: "memory")
; #define WAIT_L(n) asm volatile("s_waitcnt lgkmcnt(" #n ")" ::: "memory")
; #define BAR __builtin_amdgcn_s_barrier()
;     ...
;       LDB(B1, 1, 1); WAIT_V(0); BAR; WAIT_L(0); MMA(0, 1, At, B1); BAR;
;       LDA(At, 1, 1); BAR; WAIT_L(0); MMA(1, 0, At, B0); MMA(1, 1, At, B1); BAR; }
;     if (wr == 0) BAR;
	ds_read_b128 v[140:143], v146
	ds_read_b128 v[236:239], v146 offset:1024
	ds_read_b128 v[240:243], v146 offset:2048
	ds_read_b128 v[144:147], v146 offset:3072
	s_waitcnt vmcnt(0)
	s_barrier
	s_waitcnt lgkmcnt(0)
	s_setprio 1
	s_waitcnt lgkmcnt(0)
	v_mfma_f32_16x16x32_bf16 v[98:101], v[2:5], v[140:143], v[224:227]
	v_mfma_f32_16x16x32_bf16 v[2:5], v[2:5], v[240:243], v[90:93]
	v_mfma_f32_16x16x32_bf16 v[118:121], v[6:9], v[144:147], v[2:5]
	v_mfma_f32_16x16x32_bf16 v[2:5], v[10:13], v[140:143], v[86:89]
	v_mfma_f32_16x16x32_bf16 v[102:105], v[18:21], v[236:239], v[2:5]
	v_mfma_f32_16x16x32_bf16 v[2:5], v[10:13], v[240:243], v[164:167]
	v_mfma_f32_16x16x32_bf16 v[122:125], v[18:21], v[144:147], v[2:5]
	v_mfma_f32_16x16x32_bf16 v[2:5], v[22:25], v[140:143], v[184:187]
	v_mfma_f32_16x16x32_bf16 v[90:93], v[26:29], v[236:239], v[2:5]
	v_mfma_f32_16x16x32_bf16 v[2:5], v[22:25], v[240:243], v[188:191]
	v_mfma_f32_16x16x32_bf16 v[110:113], v[26:29], v[144:147], v[2:5]
	v_mfma_f32_16x16x32_bf16 v[2:5], v[220:223], v[140:143], v[192:195]
	v_mfma_f32_16x16x32_bf16 v[86:89], v[232:235], v[236:239], v[2:5]
	v_mfma_f32_16x16x32_bf16 v[2:5], v[220:223], v[240:243], v[196:199]
	v_mfma_f32_16x16x32_bf16 v[98:101], v[6:9], v[236:239], v[98:101]
	v_mfma_f32_16x16x32_bf16 v[106:109], v[232:235], v[144:147], v[2:5]
	s_setprio 0
	s_barrier
	ds_read_b128 v[164:167], v133 offset:49152
	ds_read_b128 v[184:187], v133 offset:50176
	ds_read_b128 v[188:191], v134 offset:49152
	ds_read_b128 v[192:195], v134 offset:50176
	ds_read_b128 v[196:199], v137 offset:49152
	ds_read_b128 v[220:223], v137 offset:50176
	ds_read_b128 v[224:227], v139 offset:49152
	ds_read_b128 v[232:235], v139 offset:50176
	s_barrier
	s_waitcnt lgkmcnt(0)
	s_setprio 1
	s_waitcnt lgkmcnt(0)
	v_mfma_f32_16x16x32_bf16 v[6:9], v[164:167], v[204:207], v[58:61]
	v_mfma_f32_16x16x32_bf16 v[10:13], v[188:191], v[204:207], v[50:53]
	v_mfma_f32_16x16x32_bf16 v[2:5], v[164:167], v[14:17], v[62:65]
	v_mfma_f32_16x16x32_bf16 v[18:21], v[184:187], v[216:219], v[6:9]
	v_mfma_f32_16x16x32_bf16 v[6:9], v[188:191], v[14:17], v[54:57]
	v_mfma_f32_16x16x32_bf16 v[22:25], v[192:195], v[216:219], v[10:13]
	v_mfma_f32_16x16x32_bf16 v[10:13], v[196:199], v[14:17], v[46:49]
	v_mfma_f32_16x16x32_bf16 v[14:17], v[224:227], v[14:17], v[38:41]
	v_mfma_f32_16x16x32_bf16 v[2:5], v[184:187], v[30:33], v[2:5]
	v_mfma_f32_16x16x32_bf16 v[6:9], v[192:195], v[30:33], v[6:9]
	v_mfma_f32_16x16x32_bf16 v[10:13], v[220:223], v[30:33], v[10:13]
	v_mfma_f32_16x16x32_bf16 v[26:29], v[196:199], v[204:207], v[42:45]
	v_mfma_f32_16x16x32_bf16 v[14:17], v[232:235], v[30:33], v[14:17]
	v_mfma_f32_16x16x32_bf16 v[30:33], v[224:227], v[204:207], v[34:37]
	v_mfma_f32_16x16x32_bf16 v[26:29], v[220:223], v[216:219], v[26:29]
	v_mfma_f32_16x16x32_bf16 v[30:33], v[232:235], v[216:219], v[30:33]
	s_setprio 0
	s_setprio 1
	v_mfma_f32_16x16x32_bf16 v[38:41], v[164:167], v[240:243], v[152:155]
	v_mfma_f32_16x16x32_bf16 v[42:45], v[188:191], v[240:243], v[160:163]
	v_mfma_f32_16x16x32_bf16 v[46:49], v[196:199], v[240:243], v[228:231]
	v_mfma_f32_16x16x32_bf16 v[34:37], v[164:167], v[140:143], v[148:151]
	v_mfma_f32_16x16x32_bf16 v[50:53], v[184:187], v[144:147], v[38:41]
	v_mfma_f32_16x16x32_bf16 v[38:41], v[188:191], v[140:143], v[156:159]
	v_mfma_f32_16x16x32_bf16 v[54:57], v[192:195], v[144:147], v[42:45]
	v_mfma_f32_16x16x32_bf16 v[42:45], v[196:199], v[140:143], v[208:211]
	v_mfma_f32_16x16x32_bf16 v[58:61], v[220:223], v[144:147], v[46:49]
	v_mfma_f32_16x16x32_bf16 v[46:49], v[224:227], v[140:143], v[212:215]
	v_mfma_f32_16x16x32_bf16 v[62:65], v[224:227], v[240:243], v[200:203]
	v_mfma_f32_16x16x32_bf16 v[34:37], v[184:187], v[236:239], v[34:37]
	v_mfma_f32_16x16x32_bf16 v[38:41], v[192:195], v[236:239], v[38:41]
	v_mfma_f32_16x16x32_bf16 v[42:45], v[220:223], v[236:239], v[42:45]
	v_mfma_f32_16x16x32_bf16 v[46:49], v[232:235], v[236:239], v[46:49]
	v_mfma_f32_16x16x32_bf16 v[62:65], v[232:235], v[144:147], v[62:65]
	s_setprio 0
	v_readlane_b32 s4, v245, 33
	v_readlane_b32 s5, v245, 34
	s_and_b64 vcc, exec, s[4:5]
	s_barrier
	s_cbranch_vccz .LBB0_421
	s_barrier
